# plus: K-loop end-of-phase scalar/address bookkeeping moved into the MFMA block so the end barrier follows the last MFMA
# speedup vs baseline: 1.0275x; 1.0008x over previous
.LBB0_270:
	s_ashr_i32 s11, s10, 31
	v_cmp_lt_i64_e32 vcc, s[14:15], v[152:153]
	s_lshl_b64 s[14:15], s[10:11], 19
	s_add_u32 s14, s68, s14
	s_addc_u32 s15, s69, s15
	s_and_b64 s[20:21], vcc, exec
	s_cselect_b32 s11, s15, s5
	s_cselect_b32 s43, s14, s4
	s_ashr_i32 s3, s2, 31
	s_lshl_b64 s[20:21], s[2:3], 19
	s_add_u32 s22, s25, s20
	s_addc_u32 s23, s36, s21
	s_and_b64 s[20:21], vcc, exec
	s_cselect_b32 s3, s23, s9
	s_cselect_b32 s73, s22, s8
	s_add_u32 s4, s4, 0x40080
	s_addc_u32 s5, s5, 0
	s_add_u32 s74, s8, 0x100
	v_mov_b32_e32 v0, 0
	s_addc_u32 s75, s9, 0
	s_mov_b32 s78, -2
	s_waitcnt lgkmcnt(0)
	s_add_u32 s8, s4, 0xfffc0080
	s_addc_u32 s9, s5, -1
	s_add_i32 s79, 0, 0x10000
	v_add_u32_e32 v142, s79, v159
	ds_read_b128 v[138:141], v142
	ds_read_b128 v[162:165], v142 offset:1024
	ds_read_b128 v[166:169], v142 offset:2048
	ds_read_b128 v[170:173], v142 offset:3072
	s_cmp_eq_u32 s78, 12
	s_cselect_b32 s21, s11, s9
	s_cselect_b32 s20, s43, s8
	s_cselect_b32 s9, s3, s75
	s_cselect_b32 s8, s73, s74
	v_lshl_add_u64 v[142:143], s[4:5], 0, v[134:135]
	s_add_i32 m0, s44, 0xc000
	ds_read_b128 v[188:191], v161
	ds_read_b128 v[196:199], v161 offset:2048
	ds_read_b128 v[204:207], v161 offset:4096
	ds_read_b128 v[212:215], v161 offset:6144
	ds_read_b128 v[192:195], v161 offset:1024
	ds_read_b128 v[200:203], v161 offset:3072
	ds_read_b128 v[208:211], v161 offset:5120
	ds_read_b128 v[216:219], v161 offset:7168
	global_load_lds_dwordx4 v[142:143], off
	v_lshl_add_u64 v[142:143], s[4:5], 0, v[136:137]
	s_add_i32 m0, s44, 0xe000
	s_nop 0
	global_load_lds_dwordx4 v[142:143], off
	s_waitcnt lgkmcnt(8)
	s_barrier
	s_setprio 1
	s_waitcnt lgkmcnt(7)
	v_mfma_f32_16x16x32_bf16 v[124:127], v[138:141], v[188:191], 0
	v_mfma_f32_16x16x32_bf16 v[120:123], v[166:169], v[188:191], 0
	s_waitcnt lgkmcnt(6)
	v_mfma_f32_16x16x32_bf16 v[108:111], v[138:141], v[196:199], 0
	v_mfma_f32_16x16x32_bf16 v[104:107], v[166:169], v[196:199], 0
	s_waitcnt lgkmcnt(5)
	v_mfma_f32_16x16x32_bf16 v[92:95], v[138:141], v[204:207], 0
	v_mfma_f32_16x16x32_bf16 v[88:91], v[166:169], v[204:207], 0
	s_waitcnt lgkmcnt(4)
	v_mfma_f32_16x16x32_bf16 v[76:79], v[138:141], v[212:215], 0
	v_mfma_f32_16x16x32_bf16 v[72:75], v[166:169], v[212:215], 0
	s_waitcnt lgkmcnt(3)
	v_mfma_f32_16x16x32_bf16 v[124:127], v[162:165], v[192:195], v[124:127]
	v_mfma_f32_16x16x32_bf16 v[120:123], v[170:173], v[192:195], v[120:123]
	s_waitcnt lgkmcnt(2)
	v_mfma_f32_16x16x32_bf16 v[108:111], v[162:165], v[200:203], v[108:111]
	v_mfma_f32_16x16x32_bf16 v[104:107], v[170:173], v[200:203], v[104:107]
	s_waitcnt lgkmcnt(1)
	v_mfma_f32_16x16x32_bf16 v[92:95], v[162:165], v[208:211], v[92:95]
	v_mfma_f32_16x16x32_bf16 v[88:91], v[170:173], v[208:211], v[88:91]
	s_waitcnt lgkmcnt(0)
	v_mfma_f32_16x16x32_bf16 v[76:79], v[162:165], v[216:219], v[76:79]
	v_mfma_f32_16x16x32_bf16 v[72:75], v[170:173], v[216:219], v[72:75]
	s_setprio 0
	s_barrier
	s_add_i32 s84, 0, 0x14000
	v_add_u32_e32 v142, s84, v159
	s_add_i32 s79, s79, s37
	ds_read_b128 v[220:223], v142
	ds_read_b128 v[224:227], v142 offset:1024
	ds_read_b128 v[228:231], v142 offset:2048
	ds_read_b128 v[232:235], v142 offset:3072
	v_lshl_add_u64 v[142:143], s[8:9], 0, v[148:149]
	s_mov_b32 m0, s79
	v_lshl_add_u64 v[174:175], s[8:9], 0, v[128:129]
	global_load_lds_dwordx4 v[142:143], off
	s_add_i32 m0, s79, 0x2000
	s_nop 0
	global_load_lds_dwordx4 v[174:175], off
	s_barrier
	s_setprio 1
	s_waitcnt lgkmcnt(3)
	v_mfma_f32_16x16x32_bf16 v[116:119], v[220:223], v[188:191], 0
	s_waitcnt lgkmcnt(1)
	v_mfma_f32_16x16x32_bf16 v[112:115], v[228:231], v[188:191], 0
	v_mfma_f32_16x16x32_bf16 v[100:103], v[220:223], v[196:199], 0
	v_mfma_f32_16x16x32_bf16 v[96:99], v[228:231], v[196:199], 0
	v_mfma_f32_16x16x32_bf16 v[84:87], v[220:223], v[204:207], 0
	v_mfma_f32_16x16x32_bf16 v[80:83], v[228:231], v[204:207], 0
	v_mfma_f32_16x16x32_bf16 v[68:71], v[220:223], v[212:215], 0
	v_mfma_f32_16x16x32_bf16 v[64:67], v[228:231], v[212:215], 0
	v_mfma_f32_16x16x32_bf16 v[116:119], v[224:227], v[192:195], v[116:119]
	s_waitcnt lgkmcnt(0)
	v_mfma_f32_16x16x32_bf16 v[112:115], v[232:235], v[192:195], v[112:115]
	v_mfma_f32_16x16x32_bf16 v[100:103], v[224:227], v[200:203], v[100:103]
	v_mfma_f32_16x16x32_bf16 v[96:99], v[232:235], v[200:203], v[96:99]
	s_mov_b32 m0, s44
	v_lshl_add_u64 v[236:237], s[20:21], 0, v[132:133]
	v_mfma_f32_16x16x32_bf16 v[84:87], v[224:227], v[208:211], v[84:87]
	v_mfma_f32_16x16x32_bf16 v[80:83], v[232:235], v[208:211], v[80:83]
	v_mfma_f32_16x16x32_bf16 v[68:71], v[224:227], v[216:219], v[68:71]
	v_mfma_f32_16x16x32_bf16 v[64:67], v[232:235], v[216:219], v[64:67]
	s_setprio 0
	s_barrier
	ds_read_b128 v[188:191], v161 offset:16384
	ds_read_b128 v[196:199], v161 offset:18432
	ds_read_b128 v[204:207], v161 offset:20480
	ds_read_b128 v[212:215], v161 offset:22528
	ds_read_b128 v[192:195], v161 offset:17408
	ds_read_b128 v[200:203], v161 offset:19456
	ds_read_b128 v[208:211], v161 offset:21504
	ds_read_b128 v[216:219], v161 offset:23552
	global_load_lds_dwordx4 v[236:237], off
	v_lshl_add_u64 v[238:239], s[20:21], 0, v[130:131]
	s_mov_b32 m0, s45
	s_nop 0
	global_load_lds_dwordx4 v[238:239], off
	s_barrier
	s_setprio 1
	s_waitcnt lgkmcnt(7)
	v_mfma_f32_16x16x32_bf16 v[60:63], v[138:141], v[188:191], 0
	v_mfma_f32_16x16x32_bf16 v[56:59], v[166:169], v[188:191], 0
	s_waitcnt lgkmcnt(6)
	v_mfma_f32_16x16x32_bf16 v[44:47], v[138:141], v[196:199], 0
	v_mfma_f32_16x16x32_bf16 v[40:43], v[166:169], v[196:199], 0
	s_waitcnt lgkmcnt(5)
	v_mfma_f32_16x16x32_bf16 v[28:31], v[138:141], v[204:207], 0
	v_mfma_f32_16x16x32_bf16 v[24:27], v[166:169], v[204:207], 0
	s_waitcnt lgkmcnt(4)
	v_mfma_f32_16x16x32_bf16 v[12:15], v[138:141], v[212:215], 0
	v_mfma_f32_16x16x32_bf16 v[8:11], v[166:169], v[212:215], 0
	s_waitcnt lgkmcnt(3)
	v_mfma_f32_16x16x32_bf16 v[60:63], v[162:165], v[192:195], v[60:63]
	v_mfma_f32_16x16x32_bf16 v[56:59], v[170:173], v[192:195], v[56:59]
	s_waitcnt lgkmcnt(2)
	v_mfma_f32_16x16x32_bf16 v[44:47], v[162:165], v[200:203], v[44:47]
	v_mfma_f32_16x16x32_bf16 v[40:43], v[170:173], v[200:203], v[40:43]
	s_waitcnt lgkmcnt(1)
	v_mfma_f32_16x16x32_bf16 v[28:31], v[162:165], v[208:211], v[28:31]
	v_mfma_f32_16x16x32_bf16 v[24:27], v[170:173], v[208:211], v[24:27]
	s_waitcnt lgkmcnt(0)
	v_mfma_f32_16x16x32_bf16 v[12:15], v[162:165], v[216:219], v[12:15]
	v_mfma_f32_16x16x32_bf16 v[8:11], v[170:173], v[216:219], v[8:11]
	s_setprio 0
	s_barrier
	s_add_u32 s80, s8, 0x40000
	s_addc_u32 s81, s9, 0
	s_add_i32 s79, s84, s37
	v_lshl_add_u64 v[138:139], s[80:81], 0, v[148:149]
	s_mov_b32 m0, s79
	s_nop 0
	global_load_lds_dwordx4 v[138:139], off
	v_lshl_add_u64 v[138:139], s[80:81], 0, v[128:129]
	s_add_i32 m0, s79, 0x2000
	s_nop 0
	global_load_lds_dwordx4 v[138:139], off
	s_waitcnt vmcnt(6)
	s_barrier
	s_setprio 1
	v_mfma_f32_16x16x32_bf16 v[52:55], v[220:223], v[188:191], 0
	v_mfma_f32_16x16x32_bf16 v[48:51], v[228:231], v[188:191], 0
	v_mfma_f32_16x16x32_bf16 v[36:39], v[220:223], v[196:199], 0
	v_mfma_f32_16x16x32_bf16 v[32:35], v[228:231], v[196:199], 0
	v_mfma_f32_16x16x32_bf16 v[20:23], v[220:223], v[204:207], 0
	v_mfma_f32_16x16x32_bf16 v[16:19], v[228:231], v[204:207], 0
	v_mfma_f32_16x16x32_bf16 v[4:7], v[220:223], v[212:215], 0
	v_mfma_f32_16x16x32_bf16 v[0:3], v[228:231], v[212:215], 0
	v_mfma_f32_16x16x32_bf16 v[52:55], v[224:227], v[192:195], v[52:55]
	v_mfma_f32_16x16x32_bf16 v[48:51], v[232:235], v[192:195], v[48:51]
	v_mfma_f32_16x16x32_bf16 v[36:39], v[224:227], v[200:203], v[36:39]
	v_mfma_f32_16x16x32_bf16 v[32:35], v[232:235], v[200:203], v[32:35]
	s_add_i32 s79, 0, 0x18000
	v_add_u32_e32 v170, s79, v159
	v_mfma_f32_16x16x32_bf16 v[20:23], v[224:227], v[208:211], v[20:23]
	v_mfma_f32_16x16x32_bf16 v[16:19], v[232:235], v[208:211], v[16:19]
	v_mfma_f32_16x16x32_bf16 v[4:7], v[224:227], v[216:219], v[4:7]
	v_mfma_f32_16x16x32_bf16 v[0:3], v[232:235], v[216:219], v[0:3]
	s_setprio 0
	s_barrier
	ds_read_b128 v[138:141], v170
	ds_read_b128 v[162:165], v170 offset:1024
	ds_read_b128 v[166:169], v170 offset:2048
	ds_read_b128 v[170:173], v170 offset:3072
	s_add_u32 s20, s20, 0x40000
	s_addc_u32 s21, s21, 0
	s_mov_b32 m0, s46
	v_lshl_add_u64 v[220:221], s[20:21], 0, v[132:133]
	ds_read_b128 v[188:191], v161 offset:32768
	ds_read_b128 v[196:199], v161 offset:34816
	ds_read_b128 v[204:207], v161 offset:36864
	ds_read_b128 v[212:215], v161 offset:38912
	ds_read_b128 v[192:195], v161 offset:33792
	ds_read_b128 v[200:203], v161 offset:35840
	ds_read_b128 v[208:211], v161 offset:37888
	ds_read_b128 v[216:219], v161 offset:39936
	global_load_lds_dwordx4 v[220:221], off
	v_lshl_add_u64 v[220:221], s[20:21], 0, v[130:131]
	s_mov_b32 m0, s47
	s_nop 0
	global_load_lds_dwordx4 v[220:221], off
	s_waitcnt lgkmcnt(8)
	s_barrier
	s_setprio 1
	s_waitcnt lgkmcnt(7)
	v_mfma_f32_16x16x32_bf16 v[124:127], v[138:141], v[188:191], v[124:127]
	v_mfma_f32_16x16x32_bf16 v[120:123], v[166:169], v[188:191], v[120:123]
	s_waitcnt lgkmcnt(6)
	v_mfma_f32_16x16x32_bf16 v[108:111], v[138:141], v[196:199], v[108:111]
	v_mfma_f32_16x16x32_bf16 v[104:107], v[166:169], v[196:199], v[104:107]
	s_waitcnt lgkmcnt(5)
	v_mfma_f32_16x16x32_bf16 v[92:95], v[138:141], v[204:207], v[92:95]
	v_mfma_f32_16x16x32_bf16 v[88:91], v[166:169], v[204:207], v[88:91]
	s_waitcnt lgkmcnt(4)
	v_mfma_f32_16x16x32_bf16 v[76:79], v[138:141], v[212:215], v[76:79]
	v_mfma_f32_16x16x32_bf16 v[72:75], v[166:169], v[212:215], v[72:75]
	s_waitcnt lgkmcnt(3)
	v_mfma_f32_16x16x32_bf16 v[124:127], v[162:165], v[192:195], v[124:127]
	v_mfma_f32_16x16x32_bf16 v[120:123], v[170:173], v[192:195], v[120:123]
	s_waitcnt lgkmcnt(2)
	v_mfma_f32_16x16x32_bf16 v[108:111], v[162:165], v[200:203], v[108:111]
	v_mfma_f32_16x16x32_bf16 v[104:107], v[170:173], v[200:203], v[104:107]
	s_waitcnt lgkmcnt(1)
	v_mfma_f32_16x16x32_bf16 v[92:95], v[162:165], v[208:211], v[92:95]
	v_mfma_f32_16x16x32_bf16 v[88:91], v[170:173], v[208:211], v[88:91]
	s_waitcnt lgkmcnt(0)
	v_mfma_f32_16x16x32_bf16 v[76:79], v[162:165], v[216:219], v[76:79]
	v_mfma_f32_16x16x32_bf16 v[72:75], v[170:173], v[216:219], v[72:75]
	s_setprio 0
	s_barrier
	s_add_i32 s20, 0, 0x1c000
	s_add_i32 s21, s79, s37
	v_add_u32_e32 v232, s20, v159
	v_lshl_add_u64 v[142:143], v[142:143], 0, s[28:29]
	s_mov_b32 m0, s21
	ds_read_b128 v[220:223], v232
	ds_read_b128 v[224:227], v232 offset:1024
	ds_read_b128 v[228:231], v232 offset:2048
	ds_read_b128 v[232:235], v232 offset:3072
	global_load_lds_dwordx4 v[142:143], off
	v_lshl_add_u64 v[142:143], v[174:175], 0, s[28:29]
	s_add_i32 m0, s21, 0x2000
	s_nop 0
	global_load_lds_dwordx4 v[142:143], off
	s_barrier
	s_setprio 1
	s_waitcnt lgkmcnt(3)
	v_mfma_f32_16x16x32_bf16 v[116:119], v[220:223], v[188:191], v[116:119]
	s_waitcnt lgkmcnt(1)
	v_mfma_f32_16x16x32_bf16 v[112:115], v[228:231], v[188:191], v[112:115]
	v_mfma_f32_16x16x32_bf16 v[100:103], v[220:223], v[196:199], v[100:103]
	v_mfma_f32_16x16x32_bf16 v[96:99], v[228:231], v[196:199], v[96:99]
	v_mfma_f32_16x16x32_bf16 v[84:87], v[220:223], v[204:207], v[84:87]
	v_mfma_f32_16x16x32_bf16 v[80:83], v[228:231], v[204:207], v[80:83]
	v_mfma_f32_16x16x32_bf16 v[68:71], v[220:223], v[212:215], v[68:71]
	v_mfma_f32_16x16x32_bf16 v[64:67], v[228:231], v[212:215], v[64:67]
	v_mfma_f32_16x16x32_bf16 v[116:119], v[224:227], v[192:195], v[116:119]
	s_waitcnt lgkmcnt(0)
	v_mfma_f32_16x16x32_bf16 v[112:115], v[232:235], v[192:195], v[112:115]
	v_mfma_f32_16x16x32_bf16 v[100:103], v[224:227], v[200:203], v[100:103]
	v_mfma_f32_16x16x32_bf16 v[96:99], v[232:235], v[200:203], v[96:99]
	s_mov_b32 m0, s51
	v_lshl_add_u64 v[142:143], v[236:237], 0, s[28:29]
	v_mfma_f32_16x16x32_bf16 v[84:87], v[224:227], v[208:211], v[84:87]
	v_mfma_f32_16x16x32_bf16 v[80:83], v[232:235], v[208:211], v[80:83]
	v_mfma_f32_16x16x32_bf16 v[68:71], v[224:227], v[216:219], v[68:71]
	v_mfma_f32_16x16x32_bf16 v[64:67], v[232:235], v[216:219], v[64:67]
	s_setprio 0
	s_barrier
	ds_read_b128 v[188:191], v161 offset:49152
	ds_read_b128 v[196:199], v161 offset:51200
	ds_read_b128 v[204:207], v161 offset:53248
	ds_read_b128 v[212:215], v161 offset:55296
	ds_read_b128 v[192:195], v161 offset:50176
	ds_read_b128 v[200:203], v161 offset:52224
	ds_read_b128 v[208:211], v161 offset:54272
	ds_read_b128 v[216:219], v161 offset:56320
	global_load_lds_dwordx4 v[142:143], off
	v_lshl_add_u64 v[142:143], v[238:239], 0, s[28:29]
	s_mov_b32 m0, s64
	s_nop 0
	global_load_lds_dwordx4 v[142:143], off
	s_barrier
	s_setprio 1
	s_waitcnt lgkmcnt(7)
	v_mfma_f32_16x16x32_bf16 v[60:63], v[138:141], v[188:191], v[60:63]
	v_mfma_f32_16x16x32_bf16 v[56:59], v[166:169], v[188:191], v[56:59]
	s_waitcnt lgkmcnt(6)
	v_mfma_f32_16x16x32_bf16 v[44:47], v[138:141], v[196:199], v[44:47]
	v_mfma_f32_16x16x32_bf16 v[40:43], v[166:169], v[196:199], v[40:43]
	s_waitcnt lgkmcnt(5)
	v_mfma_f32_16x16x32_bf16 v[28:31], v[138:141], v[204:207], v[28:31]
	v_mfma_f32_16x16x32_bf16 v[24:27], v[166:169], v[204:207], v[24:27]
	s_waitcnt lgkmcnt(4)
	v_mfma_f32_16x16x32_bf16 v[12:15], v[138:141], v[212:215], v[12:15]
	v_mfma_f32_16x16x32_bf16 v[8:11], v[166:169], v[212:215], v[8:11]
	s_waitcnt lgkmcnt(3)
	v_mfma_f32_16x16x32_bf16 v[60:63], v[162:165], v[192:195], v[60:63]
	v_mfma_f32_16x16x32_bf16 v[56:59], v[170:173], v[192:195], v[56:59]
	s_waitcnt lgkmcnt(2)
	v_mfma_f32_16x16x32_bf16 v[44:47], v[162:165], v[200:203], v[44:47]
	v_mfma_f32_16x16x32_bf16 v[40:43], v[170:173], v[200:203], v[40:43]
	s_waitcnt lgkmcnt(1)
	v_mfma_f32_16x16x32_bf16 v[28:31], v[162:165], v[208:211], v[28:31]
	v_mfma_f32_16x16x32_bf16 v[24:27], v[170:173], v[208:211], v[24:27]
	s_waitcnt lgkmcnt(0)
	v_mfma_f32_16x16x32_bf16 v[12:15], v[162:165], v[216:219], v[12:15]
	v_mfma_f32_16x16x32_bf16 v[8:11], v[170:173], v[216:219], v[8:11]
	s_setprio 0
	s_barrier
	s_add_u32 s8, s8, 0x40080
	s_addc_u32 s9, s9, 0
	s_add_i32 s20, s20, s37
	v_lshl_add_u64 v[138:139], s[8:9], 0, v[148:149]
	s_mov_b32 m0, s20
	s_nop 0
	global_load_lds_dwordx4 v[138:139], off
	v_lshl_add_u64 v[138:139], s[8:9], 0, v[128:129]
	s_add_i32 m0, s20, 0x2000
	s_nop 0
	global_load_lds_dwordx4 v[138:139], off
	s_waitcnt vmcnt(6)
	s_barrier
	s_setprio 1
	v_mfma_f32_16x16x32_bf16 v[52:55], v[220:223], v[188:191], v[52:55]
	v_mfma_f32_16x16x32_bf16 v[48:51], v[228:231], v[188:191], v[48:51]
	v_mfma_f32_16x16x32_bf16 v[36:39], v[220:223], v[196:199], v[36:39]
	v_mfma_f32_16x16x32_bf16 v[32:35], v[228:231], v[196:199], v[32:35]
	v_mfma_f32_16x16x32_bf16 v[20:23], v[220:223], v[204:207], v[20:23]
	v_mfma_f32_16x16x32_bf16 v[16:19], v[228:231], v[204:207], v[16:19]
	v_mfma_f32_16x16x32_bf16 v[4:7], v[220:223], v[212:215], v[4:7]
	v_mfma_f32_16x16x32_bf16 v[0:3], v[228:231], v[212:215], v[0:3]
	v_mfma_f32_16x16x32_bf16 v[52:55], v[224:227], v[192:195], v[52:55]
	v_mfma_f32_16x16x32_bf16 v[48:51], v[232:235], v[192:195], v[48:51]
	v_mfma_f32_16x16x32_bf16 v[36:39], v[224:227], v[200:203], v[36:39]
	v_mfma_f32_16x16x32_bf16 v[32:35], v[232:235], v[200:203], v[32:35]
	s_add_i32 s78, s78, 2
	s_add_u32 s4, s4, 0x100
	s_addc_u32 s5, s5, 0
	s_add_u32 s74, s74, 0x100
	s_addc_u32 s75, s75, 0
	s_cmp_gt_u32 s78, 13
	v_mfma_f32_16x16x32_bf16 v[20:23], v[224:227], v[208:211], v[20:23]
	v_mfma_f32_16x16x32_bf16 v[16:19], v[232:235], v[208:211], v[16:19]
	v_mfma_f32_16x16x32_bf16 v[4:7], v[224:227], v[216:219], v[4:7]
	v_mfma_f32_16x16x32_bf16 v[0:3], v[232:235], v[216:219], v[0:3]
	s_setprio 0
	s_barrier
	s_cbranch_scc1 .Lpeel_after_g0
.LBB0_271:
	s_add_u32 s8, s4, 0xfffc0080
	s_addc_u32 s9, s5, -1
	s_add_i32 s79, 0, 0x10000
	v_add_u32_e32 v142, s79, v159
	ds_read_b128 v[138:141], v142
	ds_read_b128 v[162:165], v142 offset:1024
	ds_read_b128 v[166:169], v142 offset:2048
	ds_read_b128 v[170:173], v142 offset:3072
	s_cmp_eq_u32 s78, 12
	s_cselect_b32 s21, s11, s9
	s_cselect_b32 s20, s43, s8
	s_cselect_b32 s9, s3, s75
	s_cselect_b32 s8, s73, s74
	v_lshl_add_u64 v[142:143], s[4:5], 0, v[134:135]
	s_add_i32 m0, s44, 0xc000
	ds_read_b128 v[188:191], v161
	ds_read_b128 v[196:199], v161 offset:2048
	ds_read_b128 v[204:207], v161 offset:4096
	ds_read_b128 v[212:215], v161 offset:6144
	ds_read_b128 v[192:195], v161 offset:1024
	ds_read_b128 v[200:203], v161 offset:3072
	ds_read_b128 v[208:211], v161 offset:5120
	ds_read_b128 v[216:219], v161 offset:7168
	global_load_lds_dwordx4 v[142:143], off
	v_lshl_add_u64 v[142:143], s[4:5], 0, v[136:137]
	s_add_i32 m0, s44, 0xe000
	s_nop 0
	global_load_lds_dwordx4 v[142:143], off
	s_waitcnt lgkmcnt(8)
	s_barrier
	s_setprio 1
	s_waitcnt lgkmcnt(7)
	v_mfma_f32_16x16x32_bf16 v[124:127], v[138:141], v[188:191], v[124:127]
	v_mfma_f32_16x16x32_bf16 v[120:123], v[166:169], v[188:191], v[120:123]
	s_waitcnt lgkmcnt(6)
	v_mfma_f32_16x16x32_bf16 v[108:111], v[138:141], v[196:199], v[108:111]
	v_mfma_f32_16x16x32_bf16 v[104:107], v[166:169], v[196:199], v[104:107]
	s_waitcnt lgkmcnt(5)
	v_mfma_f32_16x16x32_bf16 v[92:95], v[138:141], v[204:207], v[92:95]
	v_mfma_f32_16x16x32_bf16 v[88:91], v[166:169], v[204:207], v[88:91]
	s_waitcnt lgkmcnt(4)
	v_mfma_f32_16x16x32_bf16 v[76:79], v[138:141], v[212:215], v[76:79]
	v_mfma_f32_16x16x32_bf16 v[72:75], v[166:169], v[212:215], v[72:75]
	s_waitcnt lgkmcnt(3)
	v_mfma_f32_16x16x32_bf16 v[124:127], v[162:165], v[192:195], v[124:127]
	v_mfma_f32_16x16x32_bf16 v[120:123], v[170:173], v[192:195], v[120:123]
	s_waitcnt lgkmcnt(2)
	v_mfma_f32_16x16x32_bf16 v[108:111], v[162:165], v[200:203], v[108:111]
	v_mfma_f32_16x16x32_bf16 v[104:107], v[170:173], v[200:203], v[104:107]
	s_waitcnt lgkmcnt(1)
	v_mfma_f32_16x16x32_bf16 v[92:95], v[162:165], v[208:211], v[92:95]
	v_mfma_f32_16x16x32_bf16 v[88:91], v[170:173], v[208:211], v[88:91]
	s_waitcnt lgkmcnt(0)
	v_mfma_f32_16x16x32_bf16 v[76:79], v[162:165], v[216:219], v[76:79]
	v_mfma_f32_16x16x32_bf16 v[72:75], v[170:173], v[216:219], v[72:75]
	s_setprio 0
	s_barrier
	s_add_i32 s84, 0, 0x14000
	v_add_u32_e32 v142, s84, v159
	s_add_i32 s79, s79, s37
	ds_read_b128 v[220:223], v142
	ds_read_b128 v[224:227], v142 offset:1024
	ds_read_b128 v[228:231], v142 offset:2048
	ds_read_b128 v[232:235], v142 offset:3072
	v_lshl_add_u64 v[142:143], s[8:9], 0, v[148:149]
	s_mov_b32 m0, s79
	v_lshl_add_u64 v[174:175], s[8:9], 0, v[128:129]
	global_load_lds_dwordx4 v[142:143], off
	s_add_i32 m0, s79, 0x2000
	s_nop 0
	global_load_lds_dwordx4 v[174:175], off
	s_barrier
	s_setprio 1
	s_waitcnt lgkmcnt(3)
	v_mfma_f32_16x16x32_bf16 v[116:119], v[220:223], v[188:191], v[116:119]
	s_waitcnt lgkmcnt(1)
	v_mfma_f32_16x16x32_bf16 v[112:115], v[228:231], v[188:191], v[112:115]
	v_mfma_f32_16x16x32_bf16 v[100:103], v[220:223], v[196:199], v[100:103]
	v_mfma_f32_16x16x32_bf16 v[96:99], v[228:231], v[196:199], v[96:99]
	v_mfma_f32_16x16x32_bf16 v[84:87], v[220:223], v[204:207], v[84:87]
	v_mfma_f32_16x16x32_bf16 v[80:83], v[228:231], v[204:207], v[80:83]
	v_mfma_f32_16x16x32_bf16 v[68:71], v[220:223], v[212:215], v[68:71]
	v_mfma_f32_16x16x32_bf16 v[64:67], v[228:231], v[212:215], v[64:67]
	v_mfma_f32_16x16x32_bf16 v[116:119], v[224:227], v[192:195], v[116:119]
	s_waitcnt lgkmcnt(0)
	v_mfma_f32_16x16x32_bf16 v[112:115], v[232:235], v[192:195], v[112:115]
	v_mfma_f32_16x16x32_bf16 v[100:103], v[224:227], v[200:203], v[100:103]
	v_mfma_f32_16x16x32_bf16 v[96:99], v[232:235], v[200:203], v[96:99]
	s_mov_b32 m0, s44
	v_lshl_add_u64 v[236:237], s[20:21], 0, v[132:133]
	v_mfma_f32_16x16x32_bf16 v[84:87], v[224:227], v[208:211], v[84:87]
	v_mfma_f32_16x16x32_bf16 v[80:83], v[232:235], v[208:211], v[80:83]
	v_mfma_f32_16x16x32_bf16 v[68:71], v[224:227], v[216:219], v[68:71]
	v_mfma_f32_16x16x32_bf16 v[64:67], v[232:235], v[216:219], v[64:67]
	s_setprio 0
	s_barrier
	ds_read_b128 v[188:191], v161 offset:16384
	ds_read_b128 v[196:199], v161 offset:18432
	ds_read_b128 v[204:207], v161 offset:20480
	ds_read_b128 v[212:215], v161 offset:22528
	ds_read_b128 v[192:195], v161 offset:17408
	ds_read_b128 v[200:203], v161 offset:19456
	ds_read_b128 v[208:211], v161 offset:21504
	ds_read_b128 v[216:219], v161 offset:23552
	global_load_lds_dwordx4 v[236:237], off
	v_lshl_add_u64 v[238:239], s[20:21], 0, v[130:131]
	s_mov_b32 m0, s45
	s_nop 0
	global_load_lds_dwordx4 v[238:239], off
	s_barrier
	s_setprio 1
	s_waitcnt lgkmcnt(7)
	v_mfma_f32_16x16x32_bf16 v[60:63], v[138:141], v[188:191], v[60:63]
	v_mfma_f32_16x16x32_bf16 v[56:59], v[166:169], v[188:191], v[56:59]
	s_waitcnt lgkmcnt(6)
	v_mfma_f32_16x16x32_bf16 v[44:47], v[138:141], v[196:199], v[44:47]
	v_mfma_f32_16x16x32_bf16 v[40:43], v[166:169], v[196:199], v[40:43]
	s_waitcnt lgkmcnt(5)
	v_mfma_f32_16x16x32_bf16 v[28:31], v[138:141], v[204:207], v[28:31]
	v_mfma_f32_16x16x32_bf16 v[24:27], v[166:169], v[204:207], v[24:27]
	s_waitcnt lgkmcnt(4)
	v_mfma_f32_16x16x32_bf16 v[12:15], v[138:141], v[212:215], v[12:15]
	v_mfma_f32_16x16x32_bf16 v[8:11], v[166:169], v[212:215], v[8:11]
	s_waitcnt lgkmcnt(3)
	v_mfma_f32_16x16x32_bf16 v[60:63], v[162:165], v[192:195], v[60:63]
	v_mfma_f32_16x16x32_bf16 v[56:59], v[170:173], v[192:195], v[56:59]
	s_waitcnt lgkmcnt(2)
	v_mfma_f32_16x16x32_bf16 v[44:47], v[162:165], v[200:203], v[44:47]
	v_mfma_f32_16x16x32_bf16 v[40:43], v[170:173], v[200:203], v[40:43]
	s_waitcnt lgkmcnt(1)
	v_mfma_f32_16x16x32_bf16 v[28:31], v[162:165], v[208:211], v[28:31]
	v_mfma_f32_16x16x32_bf16 v[24:27], v[170:173], v[208:211], v[24:27]
	s_waitcnt lgkmcnt(0)
	v_mfma_f32_16x16x32_bf16 v[12:15], v[162:165], v[216:219], v[12:15]
	v_mfma_f32_16x16x32_bf16 v[8:11], v[170:173], v[216:219], v[8:11]
	s_setprio 0
	s_barrier
	s_add_u32 s80, s8, 0x40000
	s_addc_u32 s81, s9, 0
	s_add_i32 s79, s84, s37
	v_lshl_add_u64 v[138:139], s[80:81], 0, v[148:149]
	s_mov_b32 m0, s79
	s_nop 0
	global_load_lds_dwordx4 v[138:139], off
	v_lshl_add_u64 v[138:139], s[80:81], 0, v[128:129]
	s_add_i32 m0, s79, 0x2000
	s_nop 0
	global_load_lds_dwordx4 v[138:139], off
	s_waitcnt vmcnt(6)
	s_barrier
	s_setprio 1
	v_mfma_f32_16x16x32_bf16 v[52:55], v[220:223], v[188:191], v[52:55]
	v_mfma_f32_16x16x32_bf16 v[48:51], v[228:231], v[188:191], v[48:51]
	v_mfma_f32_16x16x32_bf16 v[36:39], v[220:223], v[196:199], v[36:39]
	v_mfma_f32_16x16x32_bf16 v[32:35], v[228:231], v[196:199], v[32:35]
	v_mfma_f32_16x16x32_bf16 v[20:23], v[220:223], v[204:207], v[20:23]
	v_mfma_f32_16x16x32_bf16 v[16:19], v[228:231], v[204:207], v[16:19]
	v_mfma_f32_16x16x32_bf16 v[4:7], v[220:223], v[212:215], v[4:7]
	v_mfma_f32_16x16x32_bf16 v[0:3], v[228:231], v[212:215], v[0:3]
	v_mfma_f32_16x16x32_bf16 v[52:55], v[224:227], v[192:195], v[52:55]
	v_mfma_f32_16x16x32_bf16 v[48:51], v[232:235], v[192:195], v[48:51]
	v_mfma_f32_16x16x32_bf16 v[36:39], v[224:227], v[200:203], v[36:39]
	v_mfma_f32_16x16x32_bf16 v[32:35], v[232:235], v[200:203], v[32:35]
	s_add_i32 s79, 0, 0x18000
	v_add_u32_e32 v170, s79, v159
	v_mfma_f32_16x16x32_bf16 v[20:23], v[224:227], v[208:211], v[20:23]
	v_mfma_f32_16x16x32_bf16 v[16:19], v[232:235], v[208:211], v[16:19]
	v_mfma_f32_16x16x32_bf16 v[4:7], v[224:227], v[216:219], v[4:7]
	v_mfma_f32_16x16x32_bf16 v[0:3], v[232:235], v[216:219], v[0:3]
	s_setprio 0
	s_barrier
	ds_read_b128 v[138:141], v170
	ds_read_b128 v[162:165], v170 offset:1024
	ds_read_b128 v[166:169], v170 offset:2048
	ds_read_b128 v[170:173], v170 offset:3072
	s_add_u32 s20, s20, 0x40000
	s_addc_u32 s21, s21, 0
	s_mov_b32 m0, s46
	v_lshl_add_u64 v[220:221], s[20:21], 0, v[132:133]
	ds_read_b128 v[188:191], v161 offset:32768
	ds_read_b128 v[196:199], v161 offset:34816
	ds_read_b128 v[204:207], v161 offset:36864
	ds_read_b128 v[212:215], v161 offset:38912
	ds_read_b128 v[192:195], v161 offset:33792
	ds_read_b128 v[200:203], v161 offset:35840
	ds_read_b128 v[208:211], v161 offset:37888
	ds_read_b128 v[216:219], v161 offset:39936
	global_load_lds_dwordx4 v[220:221], off
	v_lshl_add_u64 v[220:221], s[20:21], 0, v[130:131]
	s_mov_b32 m0, s47
	s_nop 0
	global_load_lds_dwordx4 v[220:221], off
	s_waitcnt lgkmcnt(8)
	s_barrier
	s_setprio 1
	s_waitcnt lgkmcnt(7)
	v_mfma_f32_16x16x32_bf16 v[124:127], v[138:141], v[188:191], v[124:127]
	v_mfma_f32_16x16x32_bf16 v[120:123], v[166:169], v[188:191], v[120:123]
	s_waitcnt lgkmcnt(6)
	v_mfma_f32_16x16x32_bf16 v[108:111], v[138:141], v[196:199], v[108:111]
	v_mfma_f32_16x16x32_bf16 v[104:107], v[166:169], v[196:199], v[104:107]
	s_waitcnt lgkmcnt(5)
	v_mfma_f32_16x16x32_bf16 v[92:95], v[138:141], v[204:207], v[92:95]
	v_mfma_f32_16x16x32_bf16 v[88:91], v[166:169], v[204:207], v[88:91]
	s_waitcnt lgkmcnt(4)
	v_mfma_f32_16x16x32_bf16 v[76:79], v[138:141], v[212:215], v[76:79]
	v_mfma_f32_16x16x32_bf16 v[72:75], v[166:169], v[212:215], v[72:75]
	s_waitcnt lgkmcnt(3)
	v_mfma_f32_16x16x32_bf16 v[124:127], v[162:165], v[192:195], v[124:127]
	v_mfma_f32_16x16x32_bf16 v[120:123], v[170:173], v[192:195], v[120:123]
	s_waitcnt lgkmcnt(2)
	v_mfma_f32_16x16x32_bf16 v[108:111], v[162:165], v[200:203], v[108:111]
	v_mfma_f32_16x16x32_bf16 v[104:107], v[170:173], v[200:203], v[104:107]
	s_waitcnt lgkmcnt(1)
	v_mfma_f32_16x16x32_bf16 v[92:95], v[162:165], v[208:211], v[92:95]
	v_mfma_f32_16x16x32_bf16 v[88:91], v[170:173], v[208:211], v[88:91]
	s_waitcnt lgkmcnt(0)
	v_mfma_f32_16x16x32_bf16 v[76:79], v[162:165], v[216:219], v[76:79]
	v_mfma_f32_16x16x32_bf16 v[72:75], v[170:173], v[216:219], v[72:75]
	s_setprio 0
	s_barrier
	s_add_i32 s20, 0, 0x1c000
	s_add_i32 s21, s79, s37
	v_add_u32_e32 v232, s20, v159
	v_lshl_add_u64 v[142:143], v[142:143], 0, s[28:29]
	s_mov_b32 m0, s21
	ds_read_b128 v[220:223], v232
	ds_read_b128 v[224:227], v232 offset:1024
	ds_read_b128 v[228:231], v232 offset:2048
	ds_read_b128 v[232:235], v232 offset:3072
	global_load_lds_dwordx4 v[142:143], off
	v_lshl_add_u64 v[142:143], v[174:175], 0, s[28:29]
	s_add_i32 m0, s21, 0x2000
	s_nop 0
	global_load_lds_dwordx4 v[142:143], off
	s_barrier
	s_setprio 1
	s_waitcnt lgkmcnt(3)
	v_mfma_f32_16x16x32_bf16 v[116:119], v[220:223], v[188:191], v[116:119]
	s_waitcnt lgkmcnt(1)
	v_mfma_f32_16x16x32_bf16 v[112:115], v[228:231], v[188:191], v[112:115]
	v_mfma_f32_16x16x32_bf16 v[100:103], v[220:223], v[196:199], v[100:103]
	v_mfma_f32_16x16x32_bf16 v[96:99], v[228:231], v[196:199], v[96:99]
	v_mfma_f32_16x16x32_bf16 v[84:87], v[220:223], v[204:207], v[84:87]
	v_mfma_f32_16x16x32_bf16 v[80:83], v[228:231], v[204:207], v[80:83]
	v_mfma_f32_16x16x32_bf16 v[68:71], v[220:223], v[212:215], v[68:71]
	v_mfma_f32_16x16x32_bf16 v[64:67], v[228:231], v[212:215], v[64:67]
	v_mfma_f32_16x16x32_bf16 v[116:119], v[224:227], v[192:195], v[116:119]
	s_waitcnt lgkmcnt(0)
	v_mfma_f32_16x16x32_bf16 v[112:115], v[232:235], v[192:195], v[112:115]
	v_mfma_f32_16x16x32_bf16 v[100:103], v[224:227], v[200:203], v[100:103]
	v_mfma_f32_16x16x32_bf16 v[96:99], v[232:235], v[200:203], v[96:99]
	s_mov_b32 m0, s51
	v_lshl_add_u64 v[142:143], v[236:237], 0, s[28:29]
	v_mfma_f32_16x16x32_bf16 v[84:87], v[224:227], v[208:211], v[84:87]
	v_mfma_f32_16x16x32_bf16 v[80:83], v[232:235], v[208:211], v[80:83]
	v_mfma_f32_16x16x32_bf16 v[68:71], v[224:227], v[216:219], v[68:71]
	v_mfma_f32_16x16x32_bf16 v[64:67], v[232:235], v[216:219], v[64:67]
	s_setprio 0
	s_barrier
	ds_read_b128 v[188:191], v161 offset:49152
	ds_read_b128 v[196:199], v161 offset:51200
	ds_read_b128 v[204:207], v161 offset:53248
	ds_read_b128 v[212:215], v161 offset:55296
	ds_read_b128 v[192:195], v161 offset:50176
	ds_read_b128 v[200:203], v161 offset:52224
	ds_read_b128 v[208:211], v161 offset:54272
	ds_read_b128 v[216:219], v161 offset:56320
	global_load_lds_dwordx4 v[142:143], off
	v_lshl_add_u64 v[142:143], v[238:239], 0, s[28:29]
	s_mov_b32 m0, s64
	s_nop 0
	global_load_lds_dwordx4 v[142:143], off
	s_barrier
	s_setprio 1
	s_waitcnt lgkmcnt(7)
	v_mfma_f32_16x16x32_bf16 v[60:63], v[138:141], v[188:191], v[60:63]
	v_mfma_f32_16x16x32_bf16 v[56:59], v[166:169], v[188:191], v[56:59]
	s_waitcnt lgkmcnt(6)
	v_mfma_f32_16x16x32_bf16 v[44:47], v[138:141], v[196:199], v[44:47]
	v_mfma_f32_16x16x32_bf16 v[40:43], v[166:169], v[196:199], v[40:43]
	s_waitcnt lgkmcnt(5)
	v_mfma_f32_16x16x32_bf16 v[28:31], v[138:141], v[204:207], v[28:31]
	v_mfma_f32_16x16x32_bf16 v[24:27], v[166:169], v[204:207], v[24:27]
	s_waitcnt lgkmcnt(4)
	v_mfma_f32_16x16x32_bf16 v[12:15], v[138:141], v[212:215], v[12:15]
	v_mfma_f32_16x16x32_bf16 v[8:11], v[166:169], v[212:215], v[8:11]
	s_waitcnt lgkmcnt(3)
	v_mfma_f32_16x16x32_bf16 v[60:63], v[162:165], v[192:195], v[60:63]
	v_mfma_f32_16x16x32_bf16 v[56:59], v[170:173], v[192:195], v[56:59]
	s_waitcnt lgkmcnt(2)
	v_mfma_f32_16x16x32_bf16 v[44:47], v[162:165], v[200:203], v[44:47]
	v_mfma_f32_16x16x32_bf16 v[40:43], v[170:173], v[200:203], v[40:43]
	s_waitcnt lgkmcnt(1)
	v_mfma_f32_16x16x32_bf16 v[28:31], v[162:165], v[208:211], v[28:31]
	v_mfma_f32_16x16x32_bf16 v[24:27], v[170:173], v[208:211], v[24:27]
	s_waitcnt lgkmcnt(0)
	v_mfma_f32_16x16x32_bf16 v[12:15], v[162:165], v[216:219], v[12:15]
	v_mfma_f32_16x16x32_bf16 v[8:11], v[170:173], v[216:219], v[8:11]
	s_setprio 0
	s_barrier
	s_add_u32 s8, s8, 0x40080
	s_addc_u32 s9, s9, 0
	s_add_i32 s20, s20, s37
	v_lshl_add_u64 v[138:139], s[8:9], 0, v[148:149]
	s_mov_b32 m0, s20
	s_nop 0
	global_load_lds_dwordx4 v[138:139], off
	v_lshl_add_u64 v[138:139], s[8:9], 0, v[128:129]
	s_add_i32 m0, s20, 0x2000
	s_nop 0
	global_load_lds_dwordx4 v[138:139], off
	s_waitcnt vmcnt(6)
	s_barrier
	s_setprio 1
	v_mfma_f32_16x16x32_bf16 v[52:55], v[220:223], v[188:191], v[52:55]
	v_mfma_f32_16x16x32_bf16 v[48:51], v[228:231], v[188:191], v[48:51]
	v_mfma_f32_16x16x32_bf16 v[36:39], v[220:223], v[196:199], v[36:39]
	v_mfma_f32_16x16x32_bf16 v[32:35], v[228:231], v[196:199], v[32:35]
	v_mfma_f32_16x16x32_bf16 v[20:23], v[220:223], v[204:207], v[20:23]
	v_mfma_f32_16x16x32_bf16 v[16:19], v[228:231], v[204:207], v[16:19]
	v_mfma_f32_16x16x32_bf16 v[4:7], v[220:223], v[212:215], v[4:7]
	v_mfma_f32_16x16x32_bf16 v[0:3], v[228:231], v[212:215], v[0:3]
	v_mfma_f32_16x16x32_bf16 v[52:55], v[224:227], v[192:195], v[52:55]
	v_mfma_f32_16x16x32_bf16 v[48:51], v[232:235], v[192:195], v[48:51]
	v_mfma_f32_16x16x32_bf16 v[36:39], v[224:227], v[200:203], v[36:39]
	v_mfma_f32_16x16x32_bf16 v[32:35], v[232:235], v[200:203], v[32:35]
	s_add_i32 s78, s78, 2
	s_add_u32 s4, s4, 0x100
	s_addc_u32 s5, s5, 0
	s_add_u32 s74, s74, 0x100
	s_addc_u32 s75, s75, 0
	s_cmp_gt_u32 s78, 13
	v_mfma_f32_16x16x32_bf16 v[20:23], v[224:227], v[208:211], v[20:23]
	v_mfma_f32_16x16x32_bf16 v[16:19], v[232:235], v[208:211], v[16:19]
	v_mfma_f32_16x16x32_bf16 v[4:7], v[224:227], v[216:219], v[4:7]
	v_mfma_f32_16x16x32_bf16 v[0:3], v[232:235], v[216:219], v[0:3]
	s_setprio 0
	s_barrier
	s_cbranch_scc0 .LBB0_271

.LBB0_489:
	s_add_u32 s0, s44, 0x80
	s_addc_u32 s1, s45, 0
	s_add_u32 vcc_lo, s42, 0x100
	v_mov_b32_e32 v0, 0
	s_addc_u32 vcc_hi, s43, 0
	s_mov_b32 s42, 0
	s_add_i32 s94, s42, 2
	s_add_u32 s44, s0, 0x80
	s_addc_u32 s43, s1, 0
	s_add_i32 s95, 0, 0x10000
	v_add_u32_e32 v140, s95, v173
	ds_read_b128 v[128:131], v140
	ds_read_b128 v[132:135], v140 offset:1024
	ds_read_b128 v[136:139], v140 offset:2048
	ds_read_b128 v[140:143], v140 offset:3072
	s_cmp_eq_u32 s79, s42
	s_cselect_b32 s42, s20, s44
	s_cselect_b32 s43, s21, s43
	s_cselect_b32 s45, s41, vcc_hi
	s_cselect_b32 s44, s40, vcc_lo
	v_lshl_add_u64 v[216:217], s[0:1], 0, v[164:165]
	s_add_i32 m0, s51, 0xc000
	ds_read_b128 v[168:171], v175
	ds_read_b128 v[192:195], v175 offset:2048
	ds_read_b128 v[200:203], v175 offset:4096
	ds_read_b128 v[208:211], v175 offset:6144
	ds_read_b128 v[188:191], v175 offset:1024
	ds_read_b128 v[196:199], v175 offset:3072
	ds_read_b128 v[204:207], v175 offset:5120
	ds_read_b128 v[212:215], v175 offset:7168
	global_load_lds_dwordx4 v[216:217], off
	v_lshl_add_u64 v[216:217], s[0:1], 0, v[166:167]
	s_add_i32 m0, s51, 0xe000
	s_nop 0
	global_load_lds_dwordx4 v[216:217], off
	s_waitcnt lgkmcnt(8)
	s_barrier
	s_setprio 1
	s_waitcnt lgkmcnt(7)
	v_mfma_f32_16x16x32_bf16 v[124:127], v[128:131], v[168:171], 0
	v_mfma_f32_16x16x32_bf16 v[120:123], v[136:139], v[168:171], 0
	s_waitcnt lgkmcnt(6)
	v_mfma_f32_16x16x32_bf16 v[112:115], v[128:131], v[192:195], 0
	v_mfma_f32_16x16x32_bf16 v[104:107], v[136:139], v[192:195], 0
	s_waitcnt lgkmcnt(5)
	v_mfma_f32_16x16x32_bf16 v[96:99], v[128:131], v[200:203], 0
	v_mfma_f32_16x16x32_bf16 v[88:91], v[136:139], v[200:203], 0
	s_waitcnt lgkmcnt(4)
	v_mfma_f32_16x16x32_bf16 v[80:83], v[128:131], v[208:211], 0
	v_mfma_f32_16x16x32_bf16 v[72:75], v[136:139], v[208:211], 0
	s_waitcnt lgkmcnt(3)
	v_mfma_f32_16x16x32_bf16 v[124:127], v[132:135], v[188:191], v[124:127]
	v_mfma_f32_16x16x32_bf16 v[120:123], v[140:143], v[188:191], v[120:123]
	s_waitcnt lgkmcnt(2)
	v_mfma_f32_16x16x32_bf16 v[112:115], v[132:135], v[196:199], v[112:115]
	v_mfma_f32_16x16x32_bf16 v[104:107], v[140:143], v[196:199], v[104:107]
	s_waitcnt lgkmcnt(1)
	v_mfma_f32_16x16x32_bf16 v[96:99], v[132:135], v[204:207], v[96:99]
	v_mfma_f32_16x16x32_bf16 v[88:91], v[140:143], v[204:207], v[88:91]
	s_waitcnt lgkmcnt(0)
	v_mfma_f32_16x16x32_bf16 v[80:83], v[132:135], v[212:215], v[80:83]
	v_mfma_f32_16x16x32_bf16 v[72:75], v[140:143], v[212:215], v[72:75]
	s_setprio 0
	s_barrier
	s_add_i32 s96, 0, 0x14000
	s_add_i32 s95, s95, s50
	v_add_u32_e32 v228, s96, v173
	v_lshl_add_u64 v[232:233], s[44:45], 0, v[148:149]
	s_mov_b32 m0, s95
	ds_read_b128 v[216:219], v228
	ds_read_b128 v[220:223], v228 offset:1024
	ds_read_b128 v[224:227], v228 offset:2048
	ds_read_b128 v[228:231], v228 offset:3072
	global_load_lds_dwordx4 v[232:233], off
	v_lshl_add_u64 v[234:235], s[44:45], 0, v[158:159]
	s_add_i32 m0, s95, 0x2000
	s_nop 0
	global_load_lds_dwordx4 v[234:235], off
	s_barrier
	s_setprio 1
	s_waitcnt lgkmcnt(3)
	v_mfma_f32_16x16x32_bf16 v[116:119], v[216:219], v[168:171], 0
	s_waitcnt lgkmcnt(1)
	v_mfma_f32_16x16x32_bf16 v[108:111], v[224:227], v[168:171], 0
	v_mfma_f32_16x16x32_bf16 v[100:103], v[216:219], v[192:195], 0
	v_mfma_f32_16x16x32_bf16 v[92:95], v[224:227], v[192:195], 0
	v_mfma_f32_16x16x32_bf16 v[84:87], v[216:219], v[200:203], 0
	v_mfma_f32_16x16x32_bf16 v[76:79], v[224:227], v[200:203], 0
	v_mfma_f32_16x16x32_bf16 v[68:71], v[216:219], v[208:211], 0
	v_mfma_f32_16x16x32_bf16 v[64:67], v[224:227], v[208:211], 0
	v_mfma_f32_16x16x32_bf16 v[116:119], v[220:223], v[188:191], v[116:119]
	s_waitcnt lgkmcnt(0)
	v_mfma_f32_16x16x32_bf16 v[108:111], v[228:231], v[188:191], v[108:111]
	v_mfma_f32_16x16x32_bf16 v[100:103], v[220:223], v[196:199], v[100:103]
	v_mfma_f32_16x16x32_bf16 v[92:95], v[228:231], v[196:199], v[92:95]
	s_mov_b32 m0, s51
	v_lshl_add_u64 v[236:237], s[42:43], 0, v[162:163]
	v_mfma_f32_16x16x32_bf16 v[84:87], v[220:223], v[204:207], v[84:87]
	v_mfma_f32_16x16x32_bf16 v[76:79], v[228:231], v[204:207], v[76:79]
	v_mfma_f32_16x16x32_bf16 v[68:71], v[220:223], v[212:215], v[68:71]
	v_mfma_f32_16x16x32_bf16 v[64:67], v[228:231], v[212:215], v[64:67]
	s_setprio 0
	s_barrier
	ds_read_b128 v[168:171], v175 offset:16384
	ds_read_b128 v[192:195], v175 offset:18432
	ds_read_b128 v[200:203], v175 offset:20480
	ds_read_b128 v[208:211], v175 offset:22528
	ds_read_b128 v[188:191], v175 offset:17408
	ds_read_b128 v[196:199], v175 offset:19456
	ds_read_b128 v[204:207], v175 offset:21504
	ds_read_b128 v[212:215], v175 offset:23552
	global_load_lds_dwordx4 v[236:237], off
	v_lshl_add_u64 v[238:239], s[42:43], 0, v[160:161]
	s_mov_b32 m0, s74
	s_nop 0
	global_load_lds_dwordx4 v[238:239], off
	s_barrier
	s_setprio 1
	s_waitcnt lgkmcnt(7)
	v_mfma_f32_16x16x32_bf16 v[60:63], v[128:131], v[168:171], 0
	v_mfma_f32_16x16x32_bf16 v[56:59], v[136:139], v[168:171], 0
	s_waitcnt lgkmcnt(6)
	v_mfma_f32_16x16x32_bf16 v[52:55], v[128:131], v[192:195], 0
	v_mfma_f32_16x16x32_bf16 v[44:47], v[136:139], v[192:195], 0
	s_waitcnt lgkmcnt(5)
	v_mfma_f32_16x16x32_bf16 v[36:39], v[128:131], v[200:203], 0
	v_mfma_f32_16x16x32_bf16 v[28:31], v[136:139], v[200:203], 0
	s_waitcnt lgkmcnt(4)
	v_mfma_f32_16x16x32_bf16 v[20:23], v[128:131], v[208:211], 0
	v_mfma_f32_16x16x32_bf16 v[12:15], v[136:139], v[208:211], 0
	s_waitcnt lgkmcnt(3)
	v_mfma_f32_16x16x32_bf16 v[60:63], v[132:135], v[188:191], v[60:63]
	v_mfma_f32_16x16x32_bf16 v[56:59], v[140:143], v[188:191], v[56:59]
	s_waitcnt lgkmcnt(2)
	v_mfma_f32_16x16x32_bf16 v[52:55], v[132:135], v[196:199], v[52:55]
	v_mfma_f32_16x16x32_bf16 v[44:47], v[140:143], v[196:199], v[44:47]
	s_waitcnt lgkmcnt(1)
	v_mfma_f32_16x16x32_bf16 v[36:39], v[132:135], v[204:207], v[36:39]
	v_mfma_f32_16x16x32_bf16 v[28:31], v[140:143], v[204:207], v[28:31]
	s_waitcnt lgkmcnt(0)
	v_mfma_f32_16x16x32_bf16 v[20:23], v[132:135], v[212:215], v[20:23]
	v_mfma_f32_16x16x32_bf16 v[12:15], v[140:143], v[212:215], v[12:15]
	s_setprio 0
	s_barrier
	s_add_u32 s44, s44, s11
	s_addc_u32 s45, s45, 0
	s_add_i32 s95, s96, s50
	v_lshl_add_u64 v[240:241], s[44:45], 0, v[148:149]
	s_mov_b32 m0, s95
	v_lshl_add_u64 v[242:243], s[44:45], 0, v[158:159]
	global_load_lds_dwordx4 v[240:241], off
	s_add_i32 m0, s95, 0x2000
	s_nop 0
	global_load_lds_dwordx4 v[242:243], off
	s_waitcnt vmcnt(6)
	s_barrier
	s_setprio 1
	v_mfma_f32_16x16x32_bf16 v[48:51], v[216:219], v[168:171], 0
	v_mfma_f32_16x16x32_bf16 v[40:43], v[224:227], v[168:171], 0
	v_mfma_f32_16x16x32_bf16 v[32:35], v[216:219], v[192:195], 0
	v_mfma_f32_16x16x32_bf16 v[24:27], v[224:227], v[192:195], 0
	v_mfma_f32_16x16x32_bf16 v[16:19], v[216:219], v[200:203], 0
	v_mfma_f32_16x16x32_bf16 v[8:11], v[224:227], v[200:203], 0
	v_mfma_f32_16x16x32_bf16 v[4:7], v[216:219], v[208:211], 0
	v_mfma_f32_16x16x32_bf16 v[0:3], v[224:227], v[208:211], 0
	v_mfma_f32_16x16x32_bf16 v[48:51], v[220:223], v[188:191], v[48:51]
	v_mfma_f32_16x16x32_bf16 v[40:43], v[228:231], v[188:191], v[40:43]
	v_mfma_f32_16x16x32_bf16 v[32:35], v[220:223], v[196:199], v[32:35]
	v_mfma_f32_16x16x32_bf16 v[24:27], v[228:231], v[196:199], v[24:27]
	s_add_i32 s44, 0, 0x18000
	v_add_u32_e32 v140, s44, v173
	v_mfma_f32_16x16x32_bf16 v[16:19], v[220:223], v[204:207], v[16:19]
	v_mfma_f32_16x16x32_bf16 v[8:11], v[228:231], v[204:207], v[8:11]
	v_mfma_f32_16x16x32_bf16 v[4:7], v[220:223], v[212:215], v[4:7]
	v_mfma_f32_16x16x32_bf16 v[0:3], v[228:231], v[212:215], v[0:3]
	s_setprio 0
	s_barrier
	ds_read_b128 v[128:131], v140
	ds_read_b128 v[132:135], v140 offset:1024
	ds_read_b128 v[136:139], v140 offset:2048
	ds_read_b128 v[140:143], v140 offset:3072
	s_add_u32 s42, s42, s84
	s_addc_u32 s43, s43, 0
	s_mov_b32 m0, s75
	v_lshl_add_u64 v[216:217], s[42:43], 0, v[162:163]
	ds_read_b128 v[168:171], v175 offset:32768
	ds_read_b128 v[192:195], v175 offset:34816
	ds_read_b128 v[200:203], v175 offset:36864
	ds_read_b128 v[208:211], v175 offset:38912
	ds_read_b128 v[188:191], v175 offset:33792
	ds_read_b128 v[196:199], v175 offset:35840
	ds_read_b128 v[204:207], v175 offset:37888
	ds_read_b128 v[212:215], v175 offset:39936
	global_load_lds_dwordx4 v[216:217], off
	v_lshl_add_u64 v[216:217], s[42:43], 0, v[160:161]
	s_mov_b32 m0, s78
	s_nop 0
	global_load_lds_dwordx4 v[216:217], off
	s_waitcnt lgkmcnt(8)
	s_barrier
	s_setprio 1
	s_waitcnt lgkmcnt(7)
	v_mfma_f32_16x16x32_bf16 v[124:127], v[128:131], v[168:171], v[124:127]
	v_mfma_f32_16x16x32_bf16 v[120:123], v[136:139], v[168:171], v[120:123]
	s_waitcnt lgkmcnt(6)
	v_mfma_f32_16x16x32_bf16 v[112:115], v[128:131], v[192:195], v[112:115]
	v_mfma_f32_16x16x32_bf16 v[104:107], v[136:139], v[192:195], v[104:107]
	s_waitcnt lgkmcnt(5)
	v_mfma_f32_16x16x32_bf16 v[96:99], v[128:131], v[200:203], v[96:99]
	v_mfma_f32_16x16x32_bf16 v[88:91], v[136:139], v[200:203], v[88:91]
	s_waitcnt lgkmcnt(4)
	v_mfma_f32_16x16x32_bf16 v[80:83], v[128:131], v[208:211], v[80:83]
	v_mfma_f32_16x16x32_bf16 v[72:75], v[136:139], v[208:211], v[72:75]
	s_waitcnt lgkmcnt(3)
	v_mfma_f32_16x16x32_bf16 v[124:127], v[132:135], v[188:191], v[124:127]
	v_mfma_f32_16x16x32_bf16 v[120:123], v[140:143], v[188:191], v[120:123]
	s_waitcnt lgkmcnt(2)
	v_mfma_f32_16x16x32_bf16 v[112:115], v[132:135], v[196:199], v[112:115]
	v_mfma_f32_16x16x32_bf16 v[104:107], v[140:143], v[196:199], v[104:107]
	s_waitcnt lgkmcnt(1)
	v_mfma_f32_16x16x32_bf16 v[96:99], v[132:135], v[204:207], v[96:99]
	v_mfma_f32_16x16x32_bf16 v[88:91], v[140:143], v[204:207], v[88:91]
	s_waitcnt lgkmcnt(0)
	v_mfma_f32_16x16x32_bf16 v[80:83], v[132:135], v[212:215], v[80:83]
	v_mfma_f32_16x16x32_bf16 v[72:75], v[140:143], v[212:215], v[72:75]
	s_setprio 0
	s_barrier
	s_add_i32 s42, 0, 0x1c000
	s_add_i32 s43, s44, s50
	v_add_u32_e32 v228, s42, v173
	v_lshl_add_u64 v[232:233], v[232:233], 0, s[28:29]
	s_mov_b32 m0, s43
	ds_read_b128 v[216:219], v228
	ds_read_b128 v[220:223], v228 offset:1024
	ds_read_b128 v[224:227], v228 offset:2048
	ds_read_b128 v[228:231], v228 offset:3072
	global_load_lds_dwordx4 v[232:233], off
	v_lshl_add_u64 v[232:233], v[234:235], 0, s[28:29]
	s_add_i32 m0, s43, 0x2000
	s_nop 0
	global_load_lds_dwordx4 v[232:233], off
	s_barrier
	s_setprio 1
	s_waitcnt lgkmcnt(3)
	v_mfma_f32_16x16x32_bf16 v[116:119], v[216:219], v[168:171], v[116:119]
	s_waitcnt lgkmcnt(1)
	v_mfma_f32_16x16x32_bf16 v[108:111], v[224:227], v[168:171], v[108:111]
	v_mfma_f32_16x16x32_bf16 v[100:103], v[216:219], v[192:195], v[100:103]
	v_mfma_f32_16x16x32_bf16 v[92:95], v[224:227], v[192:195], v[92:95]
	v_mfma_f32_16x16x32_bf16 v[84:87], v[216:219], v[200:203], v[84:87]
	v_mfma_f32_16x16x32_bf16 v[76:79], v[224:227], v[200:203], v[76:79]
	v_mfma_f32_16x16x32_bf16 v[68:71], v[216:219], v[208:211], v[68:71]
	v_mfma_f32_16x16x32_bf16 v[64:67], v[224:227], v[208:211], v[64:67]
	v_mfma_f32_16x16x32_bf16 v[116:119], v[220:223], v[188:191], v[116:119]
	s_waitcnt lgkmcnt(0)
	v_mfma_f32_16x16x32_bf16 v[108:111], v[228:231], v[188:191], v[108:111]
	v_mfma_f32_16x16x32_bf16 v[100:103], v[220:223], v[196:199], v[100:103]
	v_mfma_f32_16x16x32_bf16 v[92:95], v[228:231], v[196:199], v[92:95]
	s_mov_b32 m0, s80
	v_lshl_add_u64 v[232:233], v[236:237], 0, s[28:29]
	v_mfma_f32_16x16x32_bf16 v[84:87], v[220:223], v[204:207], v[84:87]
	v_mfma_f32_16x16x32_bf16 v[76:79], v[228:231], v[204:207], v[76:79]
	v_mfma_f32_16x16x32_bf16 v[68:71], v[220:223], v[212:215], v[68:71]
	v_mfma_f32_16x16x32_bf16 v[64:67], v[228:231], v[212:215], v[64:67]
	s_setprio 0
	s_barrier
	ds_read_b128 v[168:171], v175 offset:49152
	ds_read_b128 v[192:195], v175 offset:51200
	ds_read_b128 v[200:203], v175 offset:53248
	ds_read_b128 v[208:211], v175 offset:55296
	ds_read_b128 v[188:191], v175 offset:50176
	ds_read_b128 v[196:199], v175 offset:52224
	ds_read_b128 v[204:207], v175 offset:54272
	ds_read_b128 v[212:215], v175 offset:56320
	global_load_lds_dwordx4 v[232:233], off
	v_lshl_add_u64 v[232:233], v[238:239], 0, s[28:29]
	s_mov_b32 m0, s81
	s_nop 0
	global_load_lds_dwordx4 v[232:233], off
	s_barrier
	s_setprio 1
	s_waitcnt lgkmcnt(7)
	v_mfma_f32_16x16x32_bf16 v[60:63], v[128:131], v[168:171], v[60:63]
	v_mfma_f32_16x16x32_bf16 v[56:59], v[136:139], v[168:171], v[56:59]
	s_waitcnt lgkmcnt(6)
	v_mfma_f32_16x16x32_bf16 v[52:55], v[128:131], v[192:195], v[52:55]
	v_mfma_f32_16x16x32_bf16 v[44:47], v[136:139], v[192:195], v[44:47]
	s_waitcnt lgkmcnt(5)
	v_mfma_f32_16x16x32_bf16 v[36:39], v[128:131], v[200:203], v[36:39]
	v_mfma_f32_16x16x32_bf16 v[28:31], v[136:139], v[200:203], v[28:31]
	s_waitcnt lgkmcnt(4)
	v_mfma_f32_16x16x32_bf16 v[20:23], v[128:131], v[208:211], v[20:23]
	v_mfma_f32_16x16x32_bf16 v[12:15], v[136:139], v[208:211], v[12:15]
	s_waitcnt lgkmcnt(3)
	v_mfma_f32_16x16x32_bf16 v[60:63], v[132:135], v[188:191], v[60:63]
	v_mfma_f32_16x16x32_bf16 v[56:59], v[140:143], v[188:191], v[56:59]
	s_waitcnt lgkmcnt(2)
	v_mfma_f32_16x16x32_bf16 v[52:55], v[132:135], v[196:199], v[52:55]
	v_mfma_f32_16x16x32_bf16 v[44:47], v[140:143], v[196:199], v[44:47]
	s_waitcnt lgkmcnt(1)
	v_mfma_f32_16x16x32_bf16 v[36:39], v[132:135], v[204:207], v[36:39]
	v_mfma_f32_16x16x32_bf16 v[28:31], v[140:143], v[204:207], v[28:31]
	s_waitcnt lgkmcnt(0)
	v_mfma_f32_16x16x32_bf16 v[20:23], v[132:135], v[212:215], v[20:23]
	v_mfma_f32_16x16x32_bf16 v[12:15], v[140:143], v[212:215], v[12:15]
	s_setprio 0
	s_barrier
	s_add_i32 s42, s42, s50
	v_lshl_add_u64 v[128:129], v[240:241], 0, s[28:29]
	s_mov_b32 m0, s42
	s_nop 0
	global_load_lds_dwordx4 v[128:129], off
	v_lshl_add_u64 v[128:129], v[242:243], 0, s[28:29]
	s_add_i32 m0, s42, 0x2000
	s_nop 0
	global_load_lds_dwordx4 v[128:129], off
	s_waitcnt vmcnt(6)
	s_barrier
	s_setprio 1
	v_mfma_f32_16x16x32_bf16 v[48:51], v[216:219], v[168:171], v[48:51]
	v_mfma_f32_16x16x32_bf16 v[40:43], v[224:227], v[168:171], v[40:43]
	v_mfma_f32_16x16x32_bf16 v[32:35], v[216:219], v[192:195], v[32:35]
	v_mfma_f32_16x16x32_bf16 v[24:27], v[224:227], v[192:195], v[24:27]
	v_mfma_f32_16x16x32_bf16 v[16:19], v[216:219], v[200:203], v[16:19]
	v_mfma_f32_16x16x32_bf16 v[8:11], v[224:227], v[200:203], v[8:11]
	v_mfma_f32_16x16x32_bf16 v[4:7], v[216:219], v[208:211], v[4:7]
	v_mfma_f32_16x16x32_bf16 v[0:3], v[224:227], v[208:211], v[0:3]
	v_mfma_f32_16x16x32_bf16 v[48:51], v[220:223], v[188:191], v[48:51]
	v_mfma_f32_16x16x32_bf16 v[40:43], v[228:231], v[188:191], v[40:43]
	v_mfma_f32_16x16x32_bf16 v[32:35], v[220:223], v[196:199], v[32:35]
	v_mfma_f32_16x16x32_bf16 v[24:27], v[228:231], v[196:199], v[24:27]
	s_add_u32 s0, s0, 0x100
	s_addc_u32 s1, s1, 0
	s_add_u32 vcc_lo, vcc_lo, 0x100
	s_addc_u32 vcc_hi, vcc_hi, 0
	s_cmp_ge_u32 s94, s88
	s_mov_b32 s42, s94
	v_mfma_f32_16x16x32_bf16 v[16:19], v[220:223], v[204:207], v[16:19]
	v_mfma_f32_16x16x32_bf16 v[8:11], v[228:231], v[204:207], v[8:11]
	v_mfma_f32_16x16x32_bf16 v[4:7], v[220:223], v[212:215], v[4:7]
	v_mfma_f32_16x16x32_bf16 v[0:3], v[228:231], v[212:215], v[0:3]
	s_setprio 0
	s_barrier
	s_cbranch_scc1 .Lpeel_after_g2
.LBB0_490:
	s_add_i32 s94, s42, 2
	s_add_u32 s44, s0, 0x80
	s_addc_u32 s43, s1, 0
	s_add_i32 s95, 0, 0x10000
	v_add_u32_e32 v140, s95, v173
	ds_read_b128 v[128:131], v140
	ds_read_b128 v[132:135], v140 offset:1024
	ds_read_b128 v[136:139], v140 offset:2048
	ds_read_b128 v[140:143], v140 offset:3072
	s_cmp_eq_u32 s79, s42
	s_cselect_b32 s42, s20, s44
	s_cselect_b32 s43, s21, s43
	s_cselect_b32 s45, s41, vcc_hi
	s_cselect_b32 s44, s40, vcc_lo
	v_lshl_add_u64 v[216:217], s[0:1], 0, v[164:165]
	s_add_i32 m0, s51, 0xc000
	ds_read_b128 v[168:171], v175
	ds_read_b128 v[192:195], v175 offset:2048
	ds_read_b128 v[200:203], v175 offset:4096
	ds_read_b128 v[208:211], v175 offset:6144
	ds_read_b128 v[188:191], v175 offset:1024
	ds_read_b128 v[196:199], v175 offset:3072
	ds_read_b128 v[204:207], v175 offset:5120
	ds_read_b128 v[212:215], v175 offset:7168
	global_load_lds_dwordx4 v[216:217], off
	v_lshl_add_u64 v[216:217], s[0:1], 0, v[166:167]
	s_add_i32 m0, s51, 0xe000
	s_nop 0
	global_load_lds_dwordx4 v[216:217], off
	s_waitcnt lgkmcnt(8)
	s_barrier
	s_setprio 1
	s_waitcnt lgkmcnt(7)
	v_mfma_f32_16x16x32_bf16 v[124:127], v[128:131], v[168:171], v[124:127]
	v_mfma_f32_16x16x32_bf16 v[120:123], v[136:139], v[168:171], v[120:123]
	s_waitcnt lgkmcnt(6)
	v_mfma_f32_16x16x32_bf16 v[112:115], v[128:131], v[192:195], v[112:115]
	v_mfma_f32_16x16x32_bf16 v[104:107], v[136:139], v[192:195], v[104:107]
	s_waitcnt lgkmcnt(5)
	v_mfma_f32_16x16x32_bf16 v[96:99], v[128:131], v[200:203], v[96:99]
	v_mfma_f32_16x16x32_bf16 v[88:91], v[136:139], v[200:203], v[88:91]
	s_waitcnt lgkmcnt(4)
	v_mfma_f32_16x16x32_bf16 v[80:83], v[128:131], v[208:211], v[80:83]
	v_mfma_f32_16x16x32_bf16 v[72:75], v[136:139], v[208:211], v[72:75]
	s_waitcnt lgkmcnt(3)
	v_mfma_f32_16x16x32_bf16 v[124:127], v[132:135], v[188:191], v[124:127]
	v_mfma_f32_16x16x32_bf16 v[120:123], v[140:143], v[188:191], v[120:123]
	s_waitcnt lgkmcnt(2)
	v_mfma_f32_16x16x32_bf16 v[112:115], v[132:135], v[196:199], v[112:115]
	v_mfma_f32_16x16x32_bf16 v[104:107], v[140:143], v[196:199], v[104:107]
	s_waitcnt lgkmcnt(1)
	v_mfma_f32_16x16x32_bf16 v[96:99], v[132:135], v[204:207], v[96:99]
	v_mfma_f32_16x16x32_bf16 v[88:91], v[140:143], v[204:207], v[88:91]
	s_waitcnt lgkmcnt(0)
	v_mfma_f32_16x16x32_bf16 v[80:83], v[132:135], v[212:215], v[80:83]
	v_mfma_f32_16x16x32_bf16 v[72:75], v[140:143], v[212:215], v[72:75]
	s_setprio 0
	s_barrier
	s_add_i32 s96, 0, 0x14000
	s_add_i32 s95, s95, s50
	v_add_u32_e32 v228, s96, v173
	v_lshl_add_u64 v[232:233], s[44:45], 0, v[148:149]
	s_mov_b32 m0, s95
	ds_read_b128 v[216:219], v228
	ds_read_b128 v[220:223], v228 offset:1024
	ds_read_b128 v[224:227], v228 offset:2048
	ds_read_b128 v[228:231], v228 offset:3072
	global_load_lds_dwordx4 v[232:233], off
	v_lshl_add_u64 v[234:235], s[44:45], 0, v[158:159]
	s_add_i32 m0, s95, 0x2000
	s_nop 0
	global_load_lds_dwordx4 v[234:235], off
	s_barrier
	s_setprio 1
	s_waitcnt lgkmcnt(3)
	v_mfma_f32_16x16x32_bf16 v[116:119], v[216:219], v[168:171], v[116:119]
	s_waitcnt lgkmcnt(1)
	v_mfma_f32_16x16x32_bf16 v[108:111], v[224:227], v[168:171], v[108:111]
	v_mfma_f32_16x16x32_bf16 v[100:103], v[216:219], v[192:195], v[100:103]
	v_mfma_f32_16x16x32_bf16 v[92:95], v[224:227], v[192:195], v[92:95]
	v_mfma_f32_16x16x32_bf16 v[84:87], v[216:219], v[200:203], v[84:87]
	v_mfma_f32_16x16x32_bf16 v[76:79], v[224:227], v[200:203], v[76:79]
	v_mfma_f32_16x16x32_bf16 v[68:71], v[216:219], v[208:211], v[68:71]
	v_mfma_f32_16x16x32_bf16 v[64:67], v[224:227], v[208:211], v[64:67]
	v_mfma_f32_16x16x32_bf16 v[116:119], v[220:223], v[188:191], v[116:119]
	s_waitcnt lgkmcnt(0)
	v_mfma_f32_16x16x32_bf16 v[108:111], v[228:231], v[188:191], v[108:111]
	v_mfma_f32_16x16x32_bf16 v[100:103], v[220:223], v[196:199], v[100:103]
	v_mfma_f32_16x16x32_bf16 v[92:95], v[228:231], v[196:199], v[92:95]
	s_mov_b32 m0, s51
	v_lshl_add_u64 v[236:237], s[42:43], 0, v[162:163]
	v_mfma_f32_16x16x32_bf16 v[84:87], v[220:223], v[204:207], v[84:87]
	v_mfma_f32_16x16x32_bf16 v[76:79], v[228:231], v[204:207], v[76:79]
	v_mfma_f32_16x16x32_bf16 v[68:71], v[220:223], v[212:215], v[68:71]
	v_mfma_f32_16x16x32_bf16 v[64:67], v[228:231], v[212:215], v[64:67]
	s_setprio 0
	s_barrier
	ds_read_b128 v[168:171], v175 offset:16384
	ds_read_b128 v[192:195], v175 offset:18432
	ds_read_b128 v[200:203], v175 offset:20480
	ds_read_b128 v[208:211], v175 offset:22528
	ds_read_b128 v[188:191], v175 offset:17408
	ds_read_b128 v[196:199], v175 offset:19456
	ds_read_b128 v[204:207], v175 offset:21504
	ds_read_b128 v[212:215], v175 offset:23552
	global_load_lds_dwordx4 v[236:237], off
	v_lshl_add_u64 v[238:239], s[42:43], 0, v[160:161]
	s_mov_b32 m0, s74
	s_nop 0
	global_load_lds_dwordx4 v[238:239], off
	s_barrier
	s_setprio 1
	s_waitcnt lgkmcnt(7)
	v_mfma_f32_16x16x32_bf16 v[60:63], v[128:131], v[168:171], v[60:63]
	v_mfma_f32_16x16x32_bf16 v[56:59], v[136:139], v[168:171], v[56:59]
	s_waitcnt lgkmcnt(6)
	v_mfma_f32_16x16x32_bf16 v[52:55], v[128:131], v[192:195], v[52:55]
	v_mfma_f32_16x16x32_bf16 v[44:47], v[136:139], v[192:195], v[44:47]
	s_waitcnt lgkmcnt(5)
	v_mfma_f32_16x16x32_bf16 v[36:39], v[128:131], v[200:203], v[36:39]
	v_mfma_f32_16x16x32_bf16 v[28:31], v[136:139], v[200:203], v[28:31]
	s_waitcnt lgkmcnt(4)
	v_mfma_f32_16x16x32_bf16 v[20:23], v[128:131], v[208:211], v[20:23]
	v_mfma_f32_16x16x32_bf16 v[12:15], v[136:139], v[208:211], v[12:15]
	s_waitcnt lgkmcnt(3)
	v_mfma_f32_16x16x32_bf16 v[60:63], v[132:135], v[188:191], v[60:63]
	v_mfma_f32_16x16x32_bf16 v[56:59], v[140:143], v[188:191], v[56:59]
	s_waitcnt lgkmcnt(2)
	v_mfma_f32_16x16x32_bf16 v[52:55], v[132:135], v[196:199], v[52:55]
	v_mfma_f32_16x16x32_bf16 v[44:47], v[140:143], v[196:199], v[44:47]
	s_waitcnt lgkmcnt(1)
	v_mfma_f32_16x16x32_bf16 v[36:39], v[132:135], v[204:207], v[36:39]
	v_mfma_f32_16x16x32_bf16 v[28:31], v[140:143], v[204:207], v[28:31]
	s_waitcnt lgkmcnt(0)
	v_mfma_f32_16x16x32_bf16 v[20:23], v[132:135], v[212:215], v[20:23]
	v_mfma_f32_16x16x32_bf16 v[12:15], v[140:143], v[212:215], v[12:15]
	s_setprio 0
	s_barrier
	s_add_u32 s44, s44, s11
	s_addc_u32 s45, s45, 0
	s_add_i32 s95, s96, s50
	v_lshl_add_u64 v[240:241], s[44:45], 0, v[148:149]
	s_mov_b32 m0, s95
	v_lshl_add_u64 v[242:243], s[44:45], 0, v[158:159]
	global_load_lds_dwordx4 v[240:241], off
	s_add_i32 m0, s95, 0x2000
	s_nop 0
	global_load_lds_dwordx4 v[242:243], off
	s_waitcnt vmcnt(6)
	s_barrier
	s_setprio 1
	v_mfma_f32_16x16x32_bf16 v[48:51], v[216:219], v[168:171], v[48:51]
	v_mfma_f32_16x16x32_bf16 v[40:43], v[224:227], v[168:171], v[40:43]
	v_mfma_f32_16x16x32_bf16 v[32:35], v[216:219], v[192:195], v[32:35]
	v_mfma_f32_16x16x32_bf16 v[24:27], v[224:227], v[192:195], v[24:27]
	v_mfma_f32_16x16x32_bf16 v[16:19], v[216:219], v[200:203], v[16:19]
	v_mfma_f32_16x16x32_bf16 v[8:11], v[224:227], v[200:203], v[8:11]
	v_mfma_f32_16x16x32_bf16 v[4:7], v[216:219], v[208:211], v[4:7]
	v_mfma_f32_16x16x32_bf16 v[0:3], v[224:227], v[208:211], v[0:3]
	v_mfma_f32_16x16x32_bf16 v[48:51], v[220:223], v[188:191], v[48:51]
	v_mfma_f32_16x16x32_bf16 v[40:43], v[228:231], v[188:191], v[40:43]
	v_mfma_f32_16x16x32_bf16 v[32:35], v[220:223], v[196:199], v[32:35]
	v_mfma_f32_16x16x32_bf16 v[24:27], v[228:231], v[196:199], v[24:27]
	s_add_i32 s44, 0, 0x18000
	v_add_u32_e32 v140, s44, v173
	v_mfma_f32_16x16x32_bf16 v[16:19], v[220:223], v[204:207], v[16:19]
	v_mfma_f32_16x16x32_bf16 v[8:11], v[228:231], v[204:207], v[8:11]
	v_mfma_f32_16x16x32_bf16 v[4:7], v[220:223], v[212:215], v[4:7]
	v_mfma_f32_16x16x32_bf16 v[0:3], v[228:231], v[212:215], v[0:3]
	s_setprio 0
	s_barrier
	ds_read_b128 v[128:131], v140
	ds_read_b128 v[132:135], v140 offset:1024
	ds_read_b128 v[136:139], v140 offset:2048
	ds_read_b128 v[140:143], v140 offset:3072
	s_add_u32 s42, s42, s84
	s_addc_u32 s43, s43, 0
	s_mov_b32 m0, s75
	v_lshl_add_u64 v[216:217], s[42:43], 0, v[162:163]
	ds_read_b128 v[168:171], v175 offset:32768
	ds_read_b128 v[192:195], v175 offset:34816
	ds_read_b128 v[200:203], v175 offset:36864
	ds_read_b128 v[208:211], v175 offset:38912
	ds_read_b128 v[188:191], v175 offset:33792
	ds_read_b128 v[196:199], v175 offset:35840
	ds_read_b128 v[204:207], v175 offset:37888
	ds_read_b128 v[212:215], v175 offset:39936
	global_load_lds_dwordx4 v[216:217], off
	v_lshl_add_u64 v[216:217], s[42:43], 0, v[160:161]
	s_mov_b32 m0, s78
	s_nop 0
	global_load_lds_dwordx4 v[216:217], off
	s_waitcnt lgkmcnt(8)
	s_barrier
	s_setprio 1
	s_waitcnt lgkmcnt(7)
	v_mfma_f32_16x16x32_bf16 v[124:127], v[128:131], v[168:171], v[124:127]
	v_mfma_f32_16x16x32_bf16 v[120:123], v[136:139], v[168:171], v[120:123]
	s_waitcnt lgkmcnt(6)
	v_mfma_f32_16x16x32_bf16 v[112:115], v[128:131], v[192:195], v[112:115]
	v_mfma_f32_16x16x32_bf16 v[104:107], v[136:139], v[192:195], v[104:107]
	s_waitcnt lgkmcnt(5)
	v_mfma_f32_16x16x32_bf16 v[96:99], v[128:131], v[200:203], v[96:99]
	v_mfma_f32_16x16x32_bf16 v[88:91], v[136:139], v[200:203], v[88:91]
	s_waitcnt lgkmcnt(4)
	v_mfma_f32_16x16x32_bf16 v[80:83], v[128:131], v[208:211], v[80:83]
	v_mfma_f32_16x16x32_bf16 v[72:75], v[136:139], v[208:211], v[72:75]
	s_waitcnt lgkmcnt(3)
	v_mfma_f32_16x16x32_bf16 v[124:127], v[132:135], v[188:191], v[124:127]
	v_mfma_f32_16x16x32_bf16 v[120:123], v[140:143], v[188:191], v[120:123]
	s_waitcnt lgkmcnt(2)
	v_mfma_f32_16x16x32_bf16 v[112:115], v[132:135], v[196:199], v[112:115]
	v_mfma_f32_16x16x32_bf16 v[104:107], v[140:143], v[196:199], v[104:107]
	s_waitcnt lgkmcnt(1)
	v_mfma_f32_16x16x32_bf16 v[96:99], v[132:135], v[204:207], v[96:99]
	v_mfma_f32_16x16x32_bf16 v[88:91], v[140:143], v[204:207], v[88:91]
	s_waitcnt lgkmcnt(0)
	v_mfma_f32_16x16x32_bf16 v[80:83], v[132:135], v[212:215], v[80:83]
	v_mfma_f32_16x16x32_bf16 v[72:75], v[140:143], v[212:215], v[72:75]
	s_setprio 0
	s_barrier
	s_add_i32 s42, 0, 0x1c000
	s_add_i32 s43, s44, s50
	v_add_u32_e32 v228, s42, v173
	v_lshl_add_u64 v[232:233], v[232:233], 0, s[28:29]
	s_mov_b32 m0, s43
	ds_read_b128 v[216:219], v228
	ds_read_b128 v[220:223], v228 offset:1024
	ds_read_b128 v[224:227], v228 offset:2048
	ds_read_b128 v[228:231], v228 offset:3072
	global_load_lds_dwordx4 v[232:233], off
	v_lshl_add_u64 v[232:233], v[234:235], 0, s[28:29]
	s_add_i32 m0, s43, 0x2000
	s_nop 0
	global_load_lds_dwordx4 v[232:233], off
	s_barrier
	s_setprio 1
	s_waitcnt lgkmcnt(3)
	v_mfma_f32_16x16x32_bf16 v[116:119], v[216:219], v[168:171], v[116:119]
	s_waitcnt lgkmcnt(1)
	v_mfma_f32_16x16x32_bf16 v[108:111], v[224:227], v[168:171], v[108:111]
	v_mfma_f32_16x16x32_bf16 v[100:103], v[216:219], v[192:195], v[100:103]
	v_mfma_f32_16x16x32_bf16 v[92:95], v[224:227], v[192:195], v[92:95]
	v_mfma_f32_16x16x32_bf16 v[84:87], v[216:219], v[200:203], v[84:87]
	v_mfma_f32_16x16x32_bf16 v[76:79], v[224:227], v[200:203], v[76:79]
	v_mfma_f32_16x16x32_bf16 v[68:71], v[216:219], v[208:211], v[68:71]
	v_mfma_f32_16x16x32_bf16 v[64:67], v[224:227], v[208:211], v[64:67]
	v_mfma_f32_16x16x32_bf16 v[116:119], v[220:223], v[188:191], v[116:119]
	s_waitcnt lgkmcnt(0)
	v_mfma_f32_16x16x32_bf16 v[108:111], v[228:231], v[188:191], v[108:111]
	v_mfma_f32_16x16x32_bf16 v[100:103], v[220:223], v[196:199], v[100:103]
	v_mfma_f32_16x16x32_bf16 v[92:95], v[228:231], v[196:199], v[92:95]
	s_mov_b32 m0, s80
	v_lshl_add_u64 v[232:233], v[236:237], 0, s[28:29]
	v_mfma_f32_16x16x32_bf16 v[84:87], v[220:223], v[204:207], v[84:87]
	v_mfma_f32_16x16x32_bf16 v[76:79], v[228:231], v[204:207], v[76:79]
	v_mfma_f32_16x16x32_bf16 v[68:71], v[220:223], v[212:215], v[68:71]
	v_mfma_f32_16x16x32_bf16 v[64:67], v[228:231], v[212:215], v[64:67]
	s_setprio 0
	s_barrier
	ds_read_b128 v[168:171], v175 offset:49152
	ds_read_b128 v[192:195], v175 offset:51200
	ds_read_b128 v[200:203], v175 offset:53248
	ds_read_b128 v[208:211], v175 offset:55296
	ds_read_b128 v[188:191], v175 offset:50176
	ds_read_b128 v[196:199], v175 offset:52224
	ds_read_b128 v[204:207], v175 offset:54272
	ds_read_b128 v[212:215], v175 offset:56320
	global_load_lds_dwordx4 v[232:233], off
	v_lshl_add_u64 v[232:233], v[238:239], 0, s[28:29]
	s_mov_b32 m0, s81
	s_nop 0
	global_load_lds_dwordx4 v[232:233], off
	s_barrier
	s_setprio 1
	s_waitcnt lgkmcnt(7)
	v_mfma_f32_16x16x32_bf16 v[60:63], v[128:131], v[168:171], v[60:63]
	v_mfma_f32_16x16x32_bf16 v[56:59], v[136:139], v[168:171], v[56:59]
	s_waitcnt lgkmcnt(6)
	v_mfma_f32_16x16x32_bf16 v[52:55], v[128:131], v[192:195], v[52:55]
	v_mfma_f32_16x16x32_bf16 v[44:47], v[136:139], v[192:195], v[44:47]
	s_waitcnt lgkmcnt(5)
	v_mfma_f32_16x16x32_bf16 v[36:39], v[128:131], v[200:203], v[36:39]
	v_mfma_f32_16x16x32_bf16 v[28:31], v[136:139], v[200:203], v[28:31]
	s_waitcnt lgkmcnt(4)
	v_mfma_f32_16x16x32_bf16 v[20:23], v[128:131], v[208:211], v[20:23]
	v_mfma_f32_16x16x32_bf16 v[12:15], v[136:139], v[208:211], v[12:15]
	s_waitcnt lgkmcnt(3)
	v_mfma_f32_16x16x32_bf16 v[60:63], v[132:135], v[188:191], v[60:63]
	v_mfma_f32_16x16x32_bf16 v[56:59], v[140:143], v[188:191], v[56:59]
	s_waitcnt lgkmcnt(2)
	v_mfma_f32_16x16x32_bf16 v[52:55], v[132:135], v[196:199], v[52:55]
	v_mfma_f32_16x16x32_bf16 v[44:47], v[140:143], v[196:199], v[44:47]
	s_waitcnt lgkmcnt(1)
	v_mfma_f32_16x16x32_bf16 v[36:39], v[132:135], v[204:207], v[36:39]
	v_mfma_f32_16x16x32_bf16 v[28:31], v[140:143], v[204:207], v[28:31]
	s_waitcnt lgkmcnt(0)
	v_mfma_f32_16x16x32_bf16 v[20:23], v[132:135], v[212:215], v[20:23]
	v_mfma_f32_16x16x32_bf16 v[12:15], v[140:143], v[212:215], v[12:15]
	s_setprio 0
	s_barrier
	s_add_i32 s42, s42, s50
	v_lshl_add_u64 v[128:129], v[240:241], 0, s[28:29]
	s_mov_b32 m0, s42
	s_nop 0
	global_load_lds_dwordx4 v[128:129], off
	v_lshl_add_u64 v[128:129], v[242:243], 0, s[28:29]
	s_add_i32 m0, s42, 0x2000
	s_nop 0
	global_load_lds_dwordx4 v[128:129], off
	s_waitcnt vmcnt(6)
	s_barrier
	s_setprio 1
	v_mfma_f32_16x16x32_bf16 v[48:51], v[216:219], v[168:171], v[48:51]
	v_mfma_f32_16x16x32_bf16 v[40:43], v[224:227], v[168:171], v[40:43]
	v_mfma_f32_16x16x32_bf16 v[32:35], v[216:219], v[192:195], v[32:35]
	v_mfma_f32_16x16x32_bf16 v[24:27], v[224:227], v[192:195], v[24:27]
	v_mfma_f32_16x16x32_bf16 v[16:19], v[216:219], v[200:203], v[16:19]
	v_mfma_f32_16x16x32_bf16 v[8:11], v[224:227], v[200:203], v[8:11]
	v_mfma_f32_16x16x32_bf16 v[4:7], v[216:219], v[208:211], v[4:7]
	v_mfma_f32_16x16x32_bf16 v[0:3], v[224:227], v[208:211], v[0:3]
	v_mfma_f32_16x16x32_bf16 v[48:51], v[220:223], v[188:191], v[48:51]
	v_mfma_f32_16x16x32_bf16 v[40:43], v[228:231], v[188:191], v[40:43]
	v_mfma_f32_16x16x32_bf16 v[32:35], v[220:223], v[196:199], v[32:35]
	v_mfma_f32_16x16x32_bf16 v[24:27], v[228:231], v[196:199], v[24:27]
	s_add_u32 s0, s0, 0x100
	s_addc_u32 s1, s1, 0
	s_add_u32 vcc_lo, vcc_lo, 0x100
	s_addc_u32 vcc_hi, vcc_hi, 0
	s_cmp_ge_u32 s94, s88
	s_mov_b32 s42, s94
	v_mfma_f32_16x16x32_bf16 v[16:19], v[220:223], v[204:207], v[16:19]
	v_mfma_f32_16x16x32_bf16 v[8:11], v[228:231], v[204:207], v[8:11]
	v_mfma_f32_16x16x32_bf16 v[4:7], v[220:223], v[212:215], v[4:7]
	v_mfma_f32_16x16x32_bf16 v[0:3], v[228:231], v[212:215], v[0:3]
	s_setprio 0
	s_barrier
	s_cbranch_scc0 .LBB0_490

.LBB0_704:
	s_ashr_i32 s3, s2, 31
	v_cmp_lt_i64_e32 vcc, s[4:5], v[152:153]
	s_lshl_b64 s[4:5], s[2:3], 19
	s_add_u32 s4, s68, s4
	s_addc_u32 s5, s69, s5
	s_and_b64 s[8:9], vcc, exec
	s_cselect_b32 s3, s5, s11
	s_cselect_b32 s45, s4, s10
	s_ashr_i32 s1, s0, 31
	s_lshl_b64 s[8:9], s[0:1], 19
	s_add_u32 s8, s65, s8
	s_addc_u32 s9, s72, s9
	s_and_b64 s[20:21], vcc, exec
	s_cselect_b32 s1, s9, s15
	s_cselect_b32 s46, s8, s14
	s_add_u32 s10, s10, 0x40080
	s_addc_u32 s11, s11, 0
	s_add_u32 s47, s14, 0x100
	v_mov_b32_e32 v0, 0
	s_addc_u32 s50, s15, 0
	s_mov_b32 s51, -2
	s_add_u32 s14, s10, 0xfffc0080
	s_addc_u32 s15, s11, -1
	s_add_i32 s73, 0, 0x10000
	v_add_u32_e32 v138, s73, v141
	ds_read_b128 v[158:161], v138
	ds_read_b128 v[162:165], v138 offset:1024
	ds_read_b128 v[166:169], v138 offset:2048
	ds_read_b128 v[170:173], v138 offset:3072
	s_cmp_eq_u32 s51, 12
	s_cselect_b32 s21, s3, s15
	s_cselect_b32 s20, s45, s14
	s_cselect_b32 s15, s1, s50
	s_cselect_b32 s14, s46, s47
	v_lshl_add_u64 v[138:139], s[10:11], 0, v[134:135]
	s_add_i32 m0, s24, 0xc000
	ds_read_b128 v[188:191], v143
	ds_read_b128 v[196:199], v143 offset:2048
	ds_read_b128 v[204:207], v143 offset:4096
	ds_read_b128 v[212:215], v143 offset:6144
	ds_read_b128 v[192:195], v143 offset:1024
	ds_read_b128 v[200:203], v143 offset:3072
	ds_read_b128 v[208:211], v143 offset:5120
	ds_read_b128 v[216:219], v143 offset:7168
	global_load_lds_dwordx4 v[138:139], off
	v_lshl_add_u64 v[138:139], s[10:11], 0, v[136:137]
	s_add_i32 m0, s24, 0xe000
	s_nop 0
	global_load_lds_dwordx4 v[138:139], off
	s_waitcnt lgkmcnt(8)
	s_barrier
	s_setprio 1
	s_waitcnt lgkmcnt(7)
	v_mfma_f32_16x16x32_bf16 v[124:127], v[158:161], v[188:191], 0
	v_mfma_f32_16x16x32_bf16 v[120:123], v[166:169], v[188:191], 0
	s_waitcnt lgkmcnt(6)
	v_mfma_f32_16x16x32_bf16 v[108:111], v[158:161], v[196:199], 0
	v_mfma_f32_16x16x32_bf16 v[104:107], v[166:169], v[196:199], 0
	s_waitcnt lgkmcnt(5)
	v_mfma_f32_16x16x32_bf16 v[92:95], v[158:161], v[204:207], 0
	v_mfma_f32_16x16x32_bf16 v[88:91], v[166:169], v[204:207], 0
	s_waitcnt lgkmcnt(4)
	v_mfma_f32_16x16x32_bf16 v[76:79], v[158:161], v[212:215], 0
	v_mfma_f32_16x16x32_bf16 v[72:75], v[166:169], v[212:215], 0
	s_waitcnt lgkmcnt(3)
	v_mfma_f32_16x16x32_bf16 v[124:127], v[162:165], v[192:195], v[124:127]
	v_mfma_f32_16x16x32_bf16 v[120:123], v[170:173], v[192:195], v[120:123]
	s_waitcnt lgkmcnt(2)
	v_mfma_f32_16x16x32_bf16 v[108:111], v[162:165], v[200:203], v[108:111]
	v_mfma_f32_16x16x32_bf16 v[104:107], v[170:173], v[200:203], v[104:107]
	s_waitcnt lgkmcnt(1)
	v_mfma_f32_16x16x32_bf16 v[92:95], v[162:165], v[208:211], v[92:95]
	v_mfma_f32_16x16x32_bf16 v[88:91], v[170:173], v[208:211], v[88:91]
	s_waitcnt lgkmcnt(0)
	v_mfma_f32_16x16x32_bf16 v[76:79], v[162:165], v[216:219], v[76:79]
	v_mfma_f32_16x16x32_bf16 v[72:75], v[170:173], v[216:219], v[72:75]
	s_setprio 0
	s_barrier
	s_add_i32 s78, 0, 0x14000
	v_add_u32_e32 v138, s78, v141
	s_add_i32 s73, s73, s23
	ds_read_b128 v[220:223], v138
	ds_read_b128 v[224:227], v138 offset:1024
	ds_read_b128 v[228:231], v138 offset:2048
	ds_read_b128 v[232:235], v138 offset:3072
	v_lshl_add_u64 v[138:139], s[14:15], 0, v[148:149]
	s_mov_b32 m0, s73
	v_lshl_add_u64 v[174:175], s[14:15], 0, v[128:129]
	global_load_lds_dwordx4 v[138:139], off
	s_add_i32 m0, s73, 0x2000
	s_nop 0
	global_load_lds_dwordx4 v[174:175], off
	s_barrier
	s_setprio 1
	s_waitcnt lgkmcnt(3)
	v_mfma_f32_16x16x32_bf16 v[116:119], v[220:223], v[188:191], 0
	s_waitcnt lgkmcnt(1)
	v_mfma_f32_16x16x32_bf16 v[112:115], v[228:231], v[188:191], 0
	v_mfma_f32_16x16x32_bf16 v[100:103], v[220:223], v[196:199], 0
	v_mfma_f32_16x16x32_bf16 v[96:99], v[228:231], v[196:199], 0
	v_mfma_f32_16x16x32_bf16 v[84:87], v[220:223], v[204:207], 0
	v_mfma_f32_16x16x32_bf16 v[80:83], v[228:231], v[204:207], 0
	v_mfma_f32_16x16x32_bf16 v[68:71], v[220:223], v[212:215], 0
	v_mfma_f32_16x16x32_bf16 v[64:67], v[228:231], v[212:215], 0
	v_mfma_f32_16x16x32_bf16 v[116:119], v[224:227], v[192:195], v[116:119]
	s_waitcnt lgkmcnt(0)
	v_mfma_f32_16x16x32_bf16 v[112:115], v[232:235], v[192:195], v[112:115]
	v_mfma_f32_16x16x32_bf16 v[100:103], v[224:227], v[200:203], v[100:103]
	v_mfma_f32_16x16x32_bf16 v[96:99], v[232:235], v[200:203], v[96:99]
	s_mov_b32 m0, s24
	v_lshl_add_u64 v[236:237], s[20:21], 0, v[132:133]
	v_mfma_f32_16x16x32_bf16 v[84:87], v[224:227], v[208:211], v[84:87]
	v_mfma_f32_16x16x32_bf16 v[80:83], v[232:235], v[208:211], v[80:83]
	v_mfma_f32_16x16x32_bf16 v[68:71], v[224:227], v[216:219], v[68:71]
	v_mfma_f32_16x16x32_bf16 v[64:67], v[232:235], v[216:219], v[64:67]
	s_setprio 0
	s_barrier
	ds_read_b128 v[188:191], v143 offset:16384
	ds_read_b128 v[196:199], v143 offset:18432
	ds_read_b128 v[204:207], v143 offset:20480
	ds_read_b128 v[212:215], v143 offset:22528
	ds_read_b128 v[192:195], v143 offset:17408
	ds_read_b128 v[200:203], v143 offset:19456
	ds_read_b128 v[208:211], v143 offset:21504
	ds_read_b128 v[216:219], v143 offset:23552
	global_load_lds_dwordx4 v[236:237], off
	v_lshl_add_u64 v[238:239], s[20:21], 0, v[130:131]
	s_mov_b32 m0, s25
	s_nop 0
	global_load_lds_dwordx4 v[238:239], off
	s_barrier
	s_setprio 1
	s_waitcnt lgkmcnt(7)
	v_mfma_f32_16x16x32_bf16 v[60:63], v[158:161], v[188:191], 0
	v_mfma_f32_16x16x32_bf16 v[56:59], v[166:169], v[188:191], 0
	s_waitcnt lgkmcnt(6)
	v_mfma_f32_16x16x32_bf16 v[44:47], v[158:161], v[196:199], 0
	v_mfma_f32_16x16x32_bf16 v[40:43], v[166:169], v[196:199], 0
	s_waitcnt lgkmcnt(5)
	v_mfma_f32_16x16x32_bf16 v[28:31], v[158:161], v[204:207], 0
	v_mfma_f32_16x16x32_bf16 v[24:27], v[166:169], v[204:207], 0
	s_waitcnt lgkmcnt(4)
	v_mfma_f32_16x16x32_bf16 v[12:15], v[158:161], v[212:215], 0
	v_mfma_f32_16x16x32_bf16 v[8:11], v[166:169], v[212:215], 0
	s_waitcnt lgkmcnt(3)
	v_mfma_f32_16x16x32_bf16 v[60:63], v[162:165], v[192:195], v[60:63]
	v_mfma_f32_16x16x32_bf16 v[56:59], v[170:173], v[192:195], v[56:59]
	s_waitcnt lgkmcnt(2)
	v_mfma_f32_16x16x32_bf16 v[44:47], v[162:165], v[200:203], v[44:47]
	v_mfma_f32_16x16x32_bf16 v[40:43], v[170:173], v[200:203], v[40:43]
	s_waitcnt lgkmcnt(1)
	v_mfma_f32_16x16x32_bf16 v[28:31], v[162:165], v[208:211], v[28:31]
	v_mfma_f32_16x16x32_bf16 v[24:27], v[170:173], v[208:211], v[24:27]
	s_waitcnt lgkmcnt(0)
	v_mfma_f32_16x16x32_bf16 v[12:15], v[162:165], v[216:219], v[12:15]
	v_mfma_f32_16x16x32_bf16 v[8:11], v[170:173], v[216:219], v[8:11]
	s_setprio 0
	s_barrier
	s_add_u32 s74, s14, 0x40000
	s_addc_u32 s75, s15, 0
	s_add_i32 s73, s78, s23
	v_lshl_add_u64 v[158:159], s[74:75], 0, v[148:149]
	s_mov_b32 m0, s73
	s_nop 0
	global_load_lds_dwordx4 v[158:159], off
	v_lshl_add_u64 v[158:159], s[74:75], 0, v[128:129]
	s_add_i32 m0, s73, 0x2000
	s_nop 0
	global_load_lds_dwordx4 v[158:159], off
	s_waitcnt vmcnt(6)
	s_barrier
	s_setprio 1
	v_mfma_f32_16x16x32_bf16 v[52:55], v[220:223], v[188:191], 0
	v_mfma_f32_16x16x32_bf16 v[48:51], v[228:231], v[188:191], 0
	v_mfma_f32_16x16x32_bf16 v[36:39], v[220:223], v[196:199], 0
	v_mfma_f32_16x16x32_bf16 v[32:35], v[228:231], v[196:199], 0
	v_mfma_f32_16x16x32_bf16 v[20:23], v[220:223], v[204:207], 0
	v_mfma_f32_16x16x32_bf16 v[16:19], v[228:231], v[204:207], 0
	v_mfma_f32_16x16x32_bf16 v[4:7], v[220:223], v[212:215], 0
	v_mfma_f32_16x16x32_bf16 v[0:3], v[228:231], v[212:215], 0
	v_mfma_f32_16x16x32_bf16 v[52:55], v[224:227], v[192:195], v[52:55]
	v_mfma_f32_16x16x32_bf16 v[48:51], v[232:235], v[192:195], v[48:51]
	v_mfma_f32_16x16x32_bf16 v[36:39], v[224:227], v[200:203], v[36:39]
	v_mfma_f32_16x16x32_bf16 v[32:35], v[232:235], v[200:203], v[32:35]
	s_add_i32 s73, 0, 0x18000
	v_add_u32_e32 v170, s73, v141
	v_mfma_f32_16x16x32_bf16 v[20:23], v[224:227], v[208:211], v[20:23]
	v_mfma_f32_16x16x32_bf16 v[16:19], v[232:235], v[208:211], v[16:19]
	v_mfma_f32_16x16x32_bf16 v[4:7], v[224:227], v[216:219], v[4:7]
	v_mfma_f32_16x16x32_bf16 v[0:3], v[232:235], v[216:219], v[0:3]
	s_setprio 0
	s_barrier
	ds_read_b128 v[158:161], v170
	ds_read_b128 v[162:165], v170 offset:1024
	ds_read_b128 v[166:169], v170 offset:2048
	ds_read_b128 v[170:173], v170 offset:3072
	s_add_u32 s20, s20, 0x40000
	s_addc_u32 s21, s21, 0
	s_mov_b32 m0, s36
	v_lshl_add_u64 v[220:221], s[20:21], 0, v[132:133]
	ds_read_b128 v[188:191], v143 offset:32768
	ds_read_b128 v[196:199], v143 offset:34816
	ds_read_b128 v[204:207], v143 offset:36864
	ds_read_b128 v[212:215], v143 offset:38912
	ds_read_b128 v[192:195], v143 offset:33792
	ds_read_b128 v[200:203], v143 offset:35840
	ds_read_b128 v[208:211], v143 offset:37888
	ds_read_b128 v[216:219], v143 offset:39936
	global_load_lds_dwordx4 v[220:221], off
	v_lshl_add_u64 v[220:221], s[20:21], 0, v[130:131]
	s_mov_b32 m0, s37
	s_nop 0
	global_load_lds_dwordx4 v[220:221], off
	s_waitcnt lgkmcnt(8)
	s_barrier
	s_setprio 1
	s_waitcnt lgkmcnt(7)
	v_mfma_f32_16x16x32_bf16 v[124:127], v[158:161], v[188:191], v[124:127]
	v_mfma_f32_16x16x32_bf16 v[120:123], v[166:169], v[188:191], v[120:123]
	s_waitcnt lgkmcnt(6)
	v_mfma_f32_16x16x32_bf16 v[108:111], v[158:161], v[196:199], v[108:111]
	v_mfma_f32_16x16x32_bf16 v[104:107], v[166:169], v[196:199], v[104:107]
	s_waitcnt lgkmcnt(5)
	v_mfma_f32_16x16x32_bf16 v[92:95], v[158:161], v[204:207], v[92:95]
	v_mfma_f32_16x16x32_bf16 v[88:91], v[166:169], v[204:207], v[88:91]
	s_waitcnt lgkmcnt(4)
	v_mfma_f32_16x16x32_bf16 v[76:79], v[158:161], v[212:215], v[76:79]
	v_mfma_f32_16x16x32_bf16 v[72:75], v[166:169], v[212:215], v[72:75]
	s_waitcnt lgkmcnt(3)
	v_mfma_f32_16x16x32_bf16 v[124:127], v[162:165], v[192:195], v[124:127]
	v_mfma_f32_16x16x32_bf16 v[120:123], v[170:173], v[192:195], v[120:123]
	s_waitcnt lgkmcnt(2)
	v_mfma_f32_16x16x32_bf16 v[108:111], v[162:165], v[200:203], v[108:111]
	v_mfma_f32_16x16x32_bf16 v[104:107], v[170:173], v[200:203], v[104:107]
	s_waitcnt lgkmcnt(1)
	v_mfma_f32_16x16x32_bf16 v[92:95], v[162:165], v[208:211], v[92:95]
	v_mfma_f32_16x16x32_bf16 v[88:91], v[170:173], v[208:211], v[88:91]
	s_waitcnt lgkmcnt(0)
	v_mfma_f32_16x16x32_bf16 v[76:79], v[162:165], v[216:219], v[76:79]
	v_mfma_f32_16x16x32_bf16 v[72:75], v[170:173], v[216:219], v[72:75]
	s_setprio 0
	s_barrier
	s_add_i32 s20, 0, 0x1c000
	s_add_i32 s21, s73, s23
	v_add_u32_e32 v232, s20, v141
	v_lshl_add_u64 v[138:139], v[138:139], 0, s[28:29]
	s_mov_b32 m0, s21
	ds_read_b128 v[220:223], v232
	ds_read_b128 v[224:227], v232 offset:1024
	ds_read_b128 v[228:231], v232 offset:2048
	ds_read_b128 v[232:235], v232 offset:3072
	global_load_lds_dwordx4 v[138:139], off
	v_lshl_add_u64 v[138:139], v[174:175], 0, s[28:29]
	s_add_i32 m0, s21, 0x2000
	s_nop 0
	global_load_lds_dwordx4 v[138:139], off
	s_barrier
	s_setprio 1
	s_waitcnt lgkmcnt(3)
	v_mfma_f32_16x16x32_bf16 v[116:119], v[220:223], v[188:191], v[116:119]
	s_waitcnt lgkmcnt(1)
	v_mfma_f32_16x16x32_bf16 v[112:115], v[228:231], v[188:191], v[112:115]
	v_mfma_f32_16x16x32_bf16 v[100:103], v[220:223], v[196:199], v[100:103]
	v_mfma_f32_16x16x32_bf16 v[96:99], v[228:231], v[196:199], v[96:99]
	v_mfma_f32_16x16x32_bf16 v[84:87], v[220:223], v[204:207], v[84:87]
	v_mfma_f32_16x16x32_bf16 v[80:83], v[228:231], v[204:207], v[80:83]
	v_mfma_f32_16x16x32_bf16 v[68:71], v[220:223], v[212:215], v[68:71]
	v_mfma_f32_16x16x32_bf16 v[64:67], v[228:231], v[212:215], v[64:67]
	v_mfma_f32_16x16x32_bf16 v[116:119], v[224:227], v[192:195], v[116:119]
	s_waitcnt lgkmcnt(0)
	v_mfma_f32_16x16x32_bf16 v[112:115], v[232:235], v[192:195], v[112:115]
	v_mfma_f32_16x16x32_bf16 v[100:103], v[224:227], v[200:203], v[100:103]
	v_mfma_f32_16x16x32_bf16 v[96:99], v[232:235], v[200:203], v[96:99]
	s_mov_b32 m0, s38
	v_lshl_add_u64 v[138:139], v[236:237], 0, s[28:29]
	v_mfma_f32_16x16x32_bf16 v[84:87], v[224:227], v[208:211], v[84:87]
	v_mfma_f32_16x16x32_bf16 v[80:83], v[232:235], v[208:211], v[80:83]
	v_mfma_f32_16x16x32_bf16 v[68:71], v[224:227], v[216:219], v[68:71]
	v_mfma_f32_16x16x32_bf16 v[64:67], v[232:235], v[216:219], v[64:67]
	s_setprio 0
	s_barrier
	ds_read_b128 v[188:191], v143 offset:49152
	ds_read_b128 v[196:199], v143 offset:51200
	ds_read_b128 v[204:207], v143 offset:53248
	ds_read_b128 v[212:215], v143 offset:55296
	ds_read_b128 v[192:195], v143 offset:50176
	ds_read_b128 v[200:203], v143 offset:52224
	ds_read_b128 v[208:211], v143 offset:54272
	ds_read_b128 v[216:219], v143 offset:56320
	global_load_lds_dwordx4 v[138:139], off
	v_lshl_add_u64 v[138:139], v[238:239], 0, s[28:29]
	s_mov_b32 m0, s39
	s_nop 0
	global_load_lds_dwordx4 v[138:139], off
	s_barrier
	s_setprio 1
	s_waitcnt lgkmcnt(7)
	v_mfma_f32_16x16x32_bf16 v[60:63], v[158:161], v[188:191], v[60:63]
	v_mfma_f32_16x16x32_bf16 v[56:59], v[166:169], v[188:191], v[56:59]
	s_waitcnt lgkmcnt(6)
	v_mfma_f32_16x16x32_bf16 v[44:47], v[158:161], v[196:199], v[44:47]
	v_mfma_f32_16x16x32_bf16 v[40:43], v[166:169], v[196:199], v[40:43]
	s_waitcnt lgkmcnt(5)
	v_mfma_f32_16x16x32_bf16 v[28:31], v[158:161], v[204:207], v[28:31]
	v_mfma_f32_16x16x32_bf16 v[24:27], v[166:169], v[204:207], v[24:27]
	s_waitcnt lgkmcnt(4)
	v_mfma_f32_16x16x32_bf16 v[12:15], v[158:161], v[212:215], v[12:15]
	v_mfma_f32_16x16x32_bf16 v[8:11], v[166:169], v[212:215], v[8:11]
	s_waitcnt lgkmcnt(3)
	v_mfma_f32_16x16x32_bf16 v[60:63], v[162:165], v[192:195], v[60:63]
	v_mfma_f32_16x16x32_bf16 v[56:59], v[170:173], v[192:195], v[56:59]
	s_waitcnt lgkmcnt(2)
	v_mfma_f32_16x16x32_bf16 v[44:47], v[162:165], v[200:203], v[44:47]
	v_mfma_f32_16x16x32_bf16 v[40:43], v[170:173], v[200:203], v[40:43]
	s_waitcnt lgkmcnt(1)
	v_mfma_f32_16x16x32_bf16 v[28:31], v[162:165], v[208:211], v[28:31]
	v_mfma_f32_16x16x32_bf16 v[24:27], v[170:173], v[208:211], v[24:27]
	s_waitcnt lgkmcnt(0)
	v_mfma_f32_16x16x32_bf16 v[12:15], v[162:165], v[216:219], v[12:15]
	v_mfma_f32_16x16x32_bf16 v[8:11], v[170:173], v[216:219], v[8:11]
	s_setprio 0
	s_barrier
	s_add_u32 s14, s14, 0x40080
	s_addc_u32 s15, s15, 0
	s_add_i32 s20, s20, s23
	v_lshl_add_u64 v[138:139], s[14:15], 0, v[148:149]
	s_mov_b32 m0, s20
	s_nop 0
	global_load_lds_dwordx4 v[138:139], off
	v_lshl_add_u64 v[138:139], s[14:15], 0, v[128:129]
	s_add_i32 m0, s20, 0x2000
	s_nop 0
	global_load_lds_dwordx4 v[138:139], off
	s_waitcnt vmcnt(6)
	s_barrier
	s_setprio 1
	v_mfma_f32_16x16x32_bf16 v[52:55], v[220:223], v[188:191], v[52:55]
	v_mfma_f32_16x16x32_bf16 v[48:51], v[228:231], v[188:191], v[48:51]
	v_mfma_f32_16x16x32_bf16 v[36:39], v[220:223], v[196:199], v[36:39]
	v_mfma_f32_16x16x32_bf16 v[32:35], v[228:231], v[196:199], v[32:35]
	v_mfma_f32_16x16x32_bf16 v[20:23], v[220:223], v[204:207], v[20:23]
	v_mfma_f32_16x16x32_bf16 v[16:19], v[228:231], v[204:207], v[16:19]
	v_mfma_f32_16x16x32_bf16 v[4:7], v[220:223], v[212:215], v[4:7]
	v_mfma_f32_16x16x32_bf16 v[0:3], v[228:231], v[212:215], v[0:3]
	v_mfma_f32_16x16x32_bf16 v[52:55], v[224:227], v[192:195], v[52:55]
	v_mfma_f32_16x16x32_bf16 v[48:51], v[232:235], v[192:195], v[48:51]
	v_mfma_f32_16x16x32_bf16 v[36:39], v[224:227], v[200:203], v[36:39]
	v_mfma_f32_16x16x32_bf16 v[32:35], v[232:235], v[200:203], v[32:35]
	s_add_i32 s51, s51, 2
	s_add_u32 s10, s10, 0x100
	s_addc_u32 s11, s11, 0
	s_add_u32 s47, s47, 0x100
	s_addc_u32 s50, s50, 0
	s_cmp_gt_u32 s51, 13
	v_mfma_f32_16x16x32_bf16 v[20:23], v[224:227], v[208:211], v[20:23]
	v_mfma_f32_16x16x32_bf16 v[16:19], v[232:235], v[208:211], v[16:19]
	v_mfma_f32_16x16x32_bf16 v[4:7], v[224:227], v[216:219], v[4:7]
	v_mfma_f32_16x16x32_bf16 v[0:3], v[232:235], v[216:219], v[0:3]
	s_setprio 0
	s_barrier
	s_cbranch_scc1 .Lpeel_after_g1
.LBB0_705:
	s_add_u32 s14, s10, 0xfffc0080
	s_addc_u32 s15, s11, -1
	s_add_i32 s73, 0, 0x10000
	v_add_u32_e32 v138, s73, v141
	ds_read_b128 v[158:161], v138
	ds_read_b128 v[162:165], v138 offset:1024
	ds_read_b128 v[166:169], v138 offset:2048
	ds_read_b128 v[170:173], v138 offset:3072
	s_cmp_eq_u32 s51, 12
	s_cselect_b32 s21, s3, s15
	s_cselect_b32 s20, s45, s14
	s_cselect_b32 s15, s1, s50
	s_cselect_b32 s14, s46, s47
	v_lshl_add_u64 v[138:139], s[10:11], 0, v[134:135]
	s_add_i32 m0, s24, 0xc000
	ds_read_b128 v[188:191], v143
	ds_read_b128 v[196:199], v143 offset:2048
	ds_read_b128 v[204:207], v143 offset:4096
	ds_read_b128 v[212:215], v143 offset:6144
	ds_read_b128 v[192:195], v143 offset:1024
	ds_read_b128 v[200:203], v143 offset:3072
	ds_read_b128 v[208:211], v143 offset:5120
	ds_read_b128 v[216:219], v143 offset:7168
	global_load_lds_dwordx4 v[138:139], off
	v_lshl_add_u64 v[138:139], s[10:11], 0, v[136:137]
	s_add_i32 m0, s24, 0xe000
	s_nop 0
	global_load_lds_dwordx4 v[138:139], off
	s_waitcnt lgkmcnt(8)
	s_barrier
	s_setprio 1
	s_waitcnt lgkmcnt(7)
	v_mfma_f32_16x16x32_bf16 v[124:127], v[158:161], v[188:191], v[124:127]
	v_mfma_f32_16x16x32_bf16 v[120:123], v[166:169], v[188:191], v[120:123]
	s_waitcnt lgkmcnt(6)
	v_mfma_f32_16x16x32_bf16 v[108:111], v[158:161], v[196:199], v[108:111]
	v_mfma_f32_16x16x32_bf16 v[104:107], v[166:169], v[196:199], v[104:107]
	s_waitcnt lgkmcnt(5)
	v_mfma_f32_16x16x32_bf16 v[92:95], v[158:161], v[204:207], v[92:95]
	v_mfma_f32_16x16x32_bf16 v[88:91], v[166:169], v[204:207], v[88:91]
	s_waitcnt lgkmcnt(4)
	v_mfma_f32_16x16x32_bf16 v[76:79], v[158:161], v[212:215], v[76:79]
	v_mfma_f32_16x16x32_bf16 v[72:75], v[166:169], v[212:215], v[72:75]
	s_waitcnt lgkmcnt(3)
	v_mfma_f32_16x16x32_bf16 v[124:127], v[162:165], v[192:195], v[124:127]
	v_mfma_f32_16x16x32_bf16 v[120:123], v[170:173], v[192:195], v[120:123]
	s_waitcnt lgkmcnt(2)
	v_mfma_f32_16x16x32_bf16 v[108:111], v[162:165], v[200:203], v[108:111]
	v_mfma_f32_16x16x32_bf16 v[104:107], v[170:173], v[200:203], v[104:107]
	s_waitcnt lgkmcnt(1)
	v_mfma_f32_16x16x32_bf16 v[92:95], v[162:165], v[208:211], v[92:95]
	v_mfma_f32_16x16x32_bf16 v[88:91], v[170:173], v[208:211], v[88:91]
	s_waitcnt lgkmcnt(0)
	v_mfma_f32_16x16x32_bf16 v[76:79], v[162:165], v[216:219], v[76:79]
	v_mfma_f32_16x16x32_bf16 v[72:75], v[170:173], v[216:219], v[72:75]
	s_setprio 0
	s_barrier
	s_add_i32 s78, 0, 0x14000
	v_add_u32_e32 v138, s78, v141
	s_add_i32 s73, s73, s23
	ds_read_b128 v[220:223], v138
	ds_read_b128 v[224:227], v138 offset:1024
	ds_read_b128 v[228:231], v138 offset:2048
	ds_read_b128 v[232:235], v138 offset:3072
	v_lshl_add_u64 v[138:139], s[14:15], 0, v[148:149]
	s_mov_b32 m0, s73
	v_lshl_add_u64 v[174:175], s[14:15], 0, v[128:129]
	global_load_lds_dwordx4 v[138:139], off
	s_add_i32 m0, s73, 0x2000
	s_nop 0
	global_load_lds_dwordx4 v[174:175], off
	s_barrier
	s_setprio 1
	s_waitcnt lgkmcnt(3)
	v_mfma_f32_16x16x32_bf16 v[116:119], v[220:223], v[188:191], v[116:119]
	s_waitcnt lgkmcnt(1)
	v_mfma_f32_16x16x32_bf16 v[112:115], v[228:231], v[188:191], v[112:115]
	v_mfma_f32_16x16x32_bf16 v[100:103], v[220:223], v[196:199], v[100:103]
	v_mfma_f32_16x16x32_bf16 v[96:99], v[228:231], v[196:199], v[96:99]
	v_mfma_f32_16x16x32_bf16 v[84:87], v[220:223], v[204:207], v[84:87]
	v_mfma_f32_16x16x32_bf16 v[80:83], v[228:231], v[204:207], v[80:83]
	v_mfma_f32_16x16x32_bf16 v[68:71], v[220:223], v[212:215], v[68:71]
	v_mfma_f32_16x16x32_bf16 v[64:67], v[228:231], v[212:215], v[64:67]
	v_mfma_f32_16x16x32_bf16 v[116:119], v[224:227], v[192:195], v[116:119]
	s_waitcnt lgkmcnt(0)
	v_mfma_f32_16x16x32_bf16 v[112:115], v[232:235], v[192:195], v[112:115]
	v_mfma_f32_16x16x32_bf16 v[100:103], v[224:227], v[200:203], v[100:103]
	v_mfma_f32_16x16x32_bf16 v[96:99], v[232:235], v[200:203], v[96:99]
	s_mov_b32 m0, s24
	v_lshl_add_u64 v[236:237], s[20:21], 0, v[132:133]
	v_mfma_f32_16x16x32_bf16 v[84:87], v[224:227], v[208:211], v[84:87]
	v_mfma_f32_16x16x32_bf16 v[80:83], v[232:235], v[208:211], v[80:83]
	v_mfma_f32_16x16x32_bf16 v[68:71], v[224:227], v[216:219], v[68:71]
	v_mfma_f32_16x16x32_bf16 v[64:67], v[232:235], v[216:219], v[64:67]
	s_setprio 0
	s_barrier
	ds_read_b128 v[188:191], v143 offset:16384
	ds_read_b128 v[196:199], v143 offset:18432
	ds_read_b128 v[204:207], v143 offset:20480
	ds_read_b128 v[212:215], v143 offset:22528
	ds_read_b128 v[192:195], v143 offset:17408
	ds_read_b128 v[200:203], v143 offset:19456
	ds_read_b128 v[208:211], v143 offset:21504
	ds_read_b128 v[216:219], v143 offset:23552
	global_load_lds_dwordx4 v[236:237], off
	v_lshl_add_u64 v[238:239], s[20:21], 0, v[130:131]
	s_mov_b32 m0, s25
	s_nop 0
	global_load_lds_dwordx4 v[238:239], off
	s_barrier
	s_setprio 1
	s_waitcnt lgkmcnt(7)
	v_mfma_f32_16x16x32_bf16 v[60:63], v[158:161], v[188:191], v[60:63]
	v_mfma_f32_16x16x32_bf16 v[56:59], v[166:169], v[188:191], v[56:59]
	s_waitcnt lgkmcnt(6)
	v_mfma_f32_16x16x32_bf16 v[44:47], v[158:161], v[196:199], v[44:47]
	v_mfma_f32_16x16x32_bf16 v[40:43], v[166:169], v[196:199], v[40:43]
	s_waitcnt lgkmcnt(5)
	v_mfma_f32_16x16x32_bf16 v[28:31], v[158:161], v[204:207], v[28:31]
	v_mfma_f32_16x16x32_bf16 v[24:27], v[166:169], v[204:207], v[24:27]
	s_waitcnt lgkmcnt(4)
	v_mfma_f32_16x16x32_bf16 v[12:15], v[158:161], v[212:215], v[12:15]
	v_mfma_f32_16x16x32_bf16 v[8:11], v[166:169], v[212:215], v[8:11]
	s_waitcnt lgkmcnt(3)
	v_mfma_f32_16x16x32_bf16 v[60:63], v[162:165], v[192:195], v[60:63]
	v_mfma_f32_16x16x32_bf16 v[56:59], v[170:173], v[192:195], v[56:59]
	s_waitcnt lgkmcnt(2)
	v_mfma_f32_16x16x32_bf16 v[44:47], v[162:165], v[200:203], v[44:47]
	v_mfma_f32_16x16x32_bf16 v[40:43], v[170:173], v[200:203], v[40:43]
	s_waitcnt lgkmcnt(1)
	v_mfma_f32_16x16x32_bf16 v[28:31], v[162:165], v[208:211], v[28:31]
	v_mfma_f32_16x16x32_bf16 v[24:27], v[170:173], v[208:211], v[24:27]
	s_waitcnt lgkmcnt(0)
	v_mfma_f32_16x16x32_bf16 v[12:15], v[162:165], v[216:219], v[12:15]
	v_mfma_f32_16x16x32_bf16 v[8:11], v[170:173], v[216:219], v[8:11]
	s_setprio 0
	s_barrier
	s_add_u32 s74, s14, 0x40000
	s_addc_u32 s75, s15, 0
	s_add_i32 s73, s78, s23
	v_lshl_add_u64 v[158:159], s[74:75], 0, v[148:149]
	s_mov_b32 m0, s73
	s_nop 0
	global_load_lds_dwordx4 v[158:159], off
	v_lshl_add_u64 v[158:159], s[74:75], 0, v[128:129]
	s_add_i32 m0, s73, 0x2000
	s_nop 0
	global_load_lds_dwordx4 v[158:159], off
	s_waitcnt vmcnt(6)
	s_barrier
	s_setprio 1
	v_mfma_f32_16x16x32_bf16 v[52:55], v[220:223], v[188:191], v[52:55]
	v_mfma_f32_16x16x32_bf16 v[48:51], v[228:231], v[188:191], v[48:51]
	v_mfma_f32_16x16x32_bf16 v[36:39], v[220:223], v[196:199], v[36:39]
	v_mfma_f32_16x16x32_bf16 v[32:35], v[228:231], v[196:199], v[32:35]
	v_mfma_f32_16x16x32_bf16 v[20:23], v[220:223], v[204:207], v[20:23]
	v_mfma_f32_16x16x32_bf16 v[16:19], v[228:231], v[204:207], v[16:19]
	v_mfma_f32_16x16x32_bf16 v[4:7], v[220:223], v[212:215], v[4:7]
	v_mfma_f32_16x16x32_bf16 v[0:3], v[228:231], v[212:215], v[0:3]
	v_mfma_f32_16x16x32_bf16 v[52:55], v[224:227], v[192:195], v[52:55]
	v_mfma_f32_16x16x32_bf16 v[48:51], v[232:235], v[192:195], v[48:51]
	v_mfma_f32_16x16x32_bf16 v[36:39], v[224:227], v[200:203], v[36:39]
	v_mfma_f32_16x16x32_bf16 v[32:35], v[232:235], v[200:203], v[32:35]
	s_add_i32 s73, 0, 0x18000
	v_add_u32_e32 v170, s73, v141
	v_mfma_f32_16x16x32_bf16 v[20:23], v[224:227], v[208:211], v[20:23]
	v_mfma_f32_16x16x32_bf16 v[16:19], v[232:235], v[208:211], v[16:19]
	v_mfma_f32_16x16x32_bf16 v[4:7], v[224:227], v[216:219], v[4:7]
	v_mfma_f32_16x16x32_bf16 v[0:3], v[232:235], v[216:219], v[0:3]
	s_setprio 0
	s_barrier
	ds_read_b128 v[158:161], v170
	ds_read_b128 v[162:165], v170 offset:1024
	ds_read_b128 v[166:169], v170 offset:2048
	ds_read_b128 v[170:173], v170 offset:3072
	s_add_u32 s20, s20, 0x40000
	s_addc_u32 s21, s21, 0
	s_mov_b32 m0, s36
	v_lshl_add_u64 v[220:221], s[20:21], 0, v[132:133]
	ds_read_b128 v[188:191], v143 offset:32768
	ds_read_b128 v[196:199], v143 offset:34816
	ds_read_b128 v[204:207], v143 offset:36864
	ds_read_b128 v[212:215], v143 offset:38912
	ds_read_b128 v[192:195], v143 offset:33792
	ds_read_b128 v[200:203], v143 offset:35840
	ds_read_b128 v[208:211], v143 offset:37888
	ds_read_b128 v[216:219], v143 offset:39936
	global_load_lds_dwordx4 v[220:221], off
	v_lshl_add_u64 v[220:221], s[20:21], 0, v[130:131]
	s_mov_b32 m0, s37
	s_nop 0
	global_load_lds_dwordx4 v[220:221], off
	s_waitcnt lgkmcnt(8)
	s_barrier
	s_setprio 1
	s_waitcnt lgkmcnt(7)
	v_mfma_f32_16x16x32_bf16 v[124:127], v[158:161], v[188:191], v[124:127]
	v_mfma_f32_16x16x32_bf16 v[120:123], v[166:169], v[188:191], v[120:123]
	s_waitcnt lgkmcnt(6)
	v_mfma_f32_16x16x32_bf16 v[108:111], v[158:161], v[196:199], v[108:111]
	v_mfma_f32_16x16x32_bf16 v[104:107], v[166:169], v[196:199], v[104:107]
	s_waitcnt lgkmcnt(5)
	v_mfma_f32_16x16x32_bf16 v[92:95], v[158:161], v[204:207], v[92:95]
	v_mfma_f32_16x16x32_bf16 v[88:91], v[166:169], v[204:207], v[88:91]
	s_waitcnt lgkmcnt(4)
	v_mfma_f32_16x16x32_bf16 v[76:79], v[158:161], v[212:215], v[76:79]
	v_mfma_f32_16x16x32_bf16 v[72:75], v[166:169], v[212:215], v[72:75]
	s_waitcnt lgkmcnt(3)
	v_mfma_f32_16x16x32_bf16 v[124:127], v[162:165], v[192:195], v[124:127]
	v_mfma_f32_16x16x32_bf16 v[120:123], v[170:173], v[192:195], v[120:123]
	s_waitcnt lgkmcnt(2)
	v_mfma_f32_16x16x32_bf16 v[108:111], v[162:165], v[200:203], v[108:111]
	v_mfma_f32_16x16x32_bf16 v[104:107], v[170:173], v[200:203], v[104:107]
	s_waitcnt lgkmcnt(1)
	v_mfma_f32_16x16x32_bf16 v[92:95], v[162:165], v[208:211], v[92:95]
	v_mfma_f32_16x16x32_bf16 v[88:91], v[170:173], v[208:211], v[88:91]
	s_waitcnt lgkmcnt(0)
	v_mfma_f32_16x16x32_bf16 v[76:79], v[162:165], v[216:219], v[76:79]
	v_mfma_f32_16x16x32_bf16 v[72:75], v[170:173], v[216:219], v[72:75]
	s_setprio 0
	s_barrier
	s_add_i32 s20, 0, 0x1c000
	s_add_i32 s21, s73, s23
	v_add_u32_e32 v232, s20, v141
	v_lshl_add_u64 v[138:139], v[138:139], 0, s[28:29]
	s_mov_b32 m0, s21
	ds_read_b128 v[220:223], v232
	ds_read_b128 v[224:227], v232 offset:1024
	ds_read_b128 v[228:231], v232 offset:2048
	ds_read_b128 v[232:235], v232 offset:3072
	global_load_lds_dwordx4 v[138:139], off
	v_lshl_add_u64 v[138:139], v[174:175], 0, s[28:29]
	s_add_i32 m0, s21, 0x2000
	s_nop 0
	global_load_lds_dwordx4 v[138:139], off
	s_barrier
	s_setprio 1
	s_waitcnt lgkmcnt(3)
	v_mfma_f32_16x16x32_bf16 v[116:119], v[220:223], v[188:191], v[116:119]
	s_waitcnt lgkmcnt(1)
	v_mfma_f32_16x16x32_bf16 v[112:115], v[228:231], v[188:191], v[112:115]
	v_mfma_f32_16x16x32_bf16 v[100:103], v[220:223], v[196:199], v[100:103]
	v_mfma_f32_16x16x32_bf16 v[96:99], v[228:231], v[196:199], v[96:99]
	v_mfma_f32_16x16x32_bf16 v[84:87], v[220:223], v[204:207], v[84:87]
	v_mfma_f32_16x16x32_bf16 v[80:83], v[228:231], v[204:207], v[80:83]
	v_mfma_f32_16x16x32_bf16 v[68:71], v[220:223], v[212:215], v[68:71]
	v_mfma_f32_16x16x32_bf16 v[64:67], v[228:231], v[212:215], v[64:67]
	v_mfma_f32_16x16x32_bf16 v[116:119], v[224:227], v[192:195], v[116:119]
	s_waitcnt lgkmcnt(0)
	v_mfma_f32_16x16x32_bf16 v[112:115], v[232:235], v[192:195], v[112:115]
	v_mfma_f32_16x16x32_bf16 v[100:103], v[224:227], v[200:203], v[100:103]
	v_mfma_f32_16x16x32_bf16 v[96:99], v[232:235], v[200:203], v[96:99]
	s_mov_b32 m0, s38
	v_lshl_add_u64 v[138:139], v[236:237], 0, s[28:29]
	v_mfma_f32_16x16x32_bf16 v[84:87], v[224:227], v[208:211], v[84:87]
	v_mfma_f32_16x16x32_bf16 v[80:83], v[232:235], v[208:211], v[80:83]
	v_mfma_f32_16x16x32_bf16 v[68:71], v[224:227], v[216:219], v[68:71]
	v_mfma_f32_16x16x32_bf16 v[64:67], v[232:235], v[216:219], v[64:67]
	s_setprio 0
	s_barrier
	ds_read_b128 v[188:191], v143 offset:49152
	ds_read_b128 v[196:199], v143 offset:51200
	ds_read_b128 v[204:207], v143 offset:53248
	ds_read_b128 v[212:215], v143 offset:55296
	ds_read_b128 v[192:195], v143 offset:50176
	ds_read_b128 v[200:203], v143 offset:52224
	ds_read_b128 v[208:211], v143 offset:54272
	ds_read_b128 v[216:219], v143 offset:56320
	global_load_lds_dwordx4 v[138:139], off
	v_lshl_add_u64 v[138:139], v[238:239], 0, s[28:29]
	s_mov_b32 m0, s39
	s_nop 0
	global_load_lds_dwordx4 v[138:139], off
	s_barrier
	s_setprio 1
	s_waitcnt lgkmcnt(7)
	v_mfma_f32_16x16x32_bf16 v[60:63], v[158:161], v[188:191], v[60:63]
	v_mfma_f32_16x16x32_bf16 v[56:59], v[166:169], v[188:191], v[56:59]
	s_waitcnt lgkmcnt(6)
	v_mfma_f32_16x16x32_bf16 v[44:47], v[158:161], v[196:199], v[44:47]
	v_mfma_f32_16x16x32_bf16 v[40:43], v[166:169], v[196:199], v[40:43]
	s_waitcnt lgkmcnt(5)
	v_mfma_f32_16x16x32_bf16 v[28:31], v[158:161], v[204:207], v[28:31]
	v_mfma_f32_16x16x32_bf16 v[24:27], v[166:169], v[204:207], v[24:27]
	s_waitcnt lgkmcnt(4)
	v_mfma_f32_16x16x32_bf16 v[12:15], v[158:161], v[212:215], v[12:15]
	v_mfma_f32_16x16x32_bf16 v[8:11], v[166:169], v[212:215], v[8:11]
	s_waitcnt lgkmcnt(3)
	v_mfma_f32_16x16x32_bf16 v[60:63], v[162:165], v[192:195], v[60:63]
	v_mfma_f32_16x16x32_bf16 v[56:59], v[170:173], v[192:195], v[56:59]
	s_waitcnt lgkmcnt(2)
	v_mfma_f32_16x16x32_bf16 v[44:47], v[162:165], v[200:203], v[44:47]
	v_mfma_f32_16x16x32_bf16 v[40:43], v[170:173], v[200:203], v[40:43]
	s_waitcnt lgkmcnt(1)
	v_mfma_f32_16x16x32_bf16 v[28:31], v[162:165], v[208:211], v[28:31]
	v_mfma_f32_16x16x32_bf16 v[24:27], v[170:173], v[208:211], v[24:27]
	s_waitcnt lgkmcnt(0)
	v_mfma_f32_16x16x32_bf16 v[12:15], v[162:165], v[216:219], v[12:15]
	v_mfma_f32_16x16x32_bf16 v[8:11], v[170:173], v[216:219], v[8:11]
	s_setprio 0
	s_barrier
	s_add_u32 s14, s14, 0x40080
	s_addc_u32 s15, s15, 0
	s_add_i32 s20, s20, s23
	v_lshl_add_u64 v[138:139], s[14:15], 0, v[148:149]
	s_mov_b32 m0, s20
	s_nop 0
	global_load_lds_dwordx4 v[138:139], off
	v_lshl_add_u64 v[138:139], s[14:15], 0, v[128:129]
	s_add_i32 m0, s20, 0x2000
	s_nop 0
	global_load_lds_dwordx4 v[138:139], off
	s_waitcnt vmcnt(6)
	s_barrier
	s_setprio 1
	v_mfma_f32_16x16x32_bf16 v[52:55], v[220:223], v[188:191], v[52:55]
	v_mfma_f32_16x16x32_bf16 v[48:51], v[228:231], v[188:191], v[48:51]
	v_mfma_f32_16x16x32_bf16 v[36:39], v[220:223], v[196:199], v[36:39]
	v_mfma_f32_16x16x32_bf16 v[32:35], v[228:231], v[196:199], v[32:35]
	v_mfma_f32_16x16x32_bf16 v[20:23], v[220:223], v[204:207], v[20:23]
	v_mfma_f32_16x16x32_bf16 v[16:19], v[228:231], v[204:207], v[16:19]
	v_mfma_f32_16x16x32_bf16 v[4:7], v[220:223], v[212:215], v[4:7]
	v_mfma_f32_16x16x32_bf16 v[0:3], v[228:231], v[212:215], v[0:3]
	v_mfma_f32_16x16x32_bf16 v[52:55], v[224:227], v[192:195], v[52:55]
	v_mfma_f32_16x16x32_bf16 v[48:51], v[232:235], v[192:195], v[48:51]
	v_mfma_f32_16x16x32_bf16 v[36:39], v[224:227], v[200:203], v[36:39]
	v_mfma_f32_16x16x32_bf16 v[32:35], v[232:235], v[200:203], v[32:35]
	s_add_i32 s51, s51, 2
	s_add_u32 s10, s10, 0x100
	s_addc_u32 s11, s11, 0
	s_add_u32 s47, s47, 0x100
	s_addc_u32 s50, s50, 0
	s_cmp_gt_u32 s51, 13
	v_mfma_f32_16x16x32_bf16 v[20:23], v[224:227], v[208:211], v[20:23]
	v_mfma_f32_16x16x32_bf16 v[16:19], v[232:235], v[208:211], v[16:19]
	v_mfma_f32_16x16x32_bf16 v[4:7], v[224:227], v[216:219], v[4:7]
	v_mfma_f32_16x16x32_bf16 v[0:3], v[232:235], v[216:219], v[0:3]
	s_setprio 0
	s_barrier
	s_cbranch_scc0 .LBB0_705
